# GEMV core (adaLN modulation and shift@W phases): 8 weight-row loads of each k-group issued together with counted vmcnt instead of one at a time; norm_first row loop loads issued together
# speedup vs baseline: 1.0142x; 1.0115x over previous
; #define LAS __attribute__((address_space(3)))
; __device__ __forceinline__ void gemv24_item(const float* W, int N, int j0, LAS float* sc, LAS float* red, float (&res)[6], const int tid) {
;     ...
;     for (int kk = 0; kk < 64; ++kk) {
;         const f32x4 wv = *(const f32x4*)(w + (size_t)kk * N);
;         const LAS f32x4* s4 = (const LAS f32x4*)(sc + (ks * 64 + kk) * 24);
; #pragma unroll
;         for (int b4 = 0; b4 < 6; ++b4) { const f32x4 s = s4[b4]; acc[4 * b4] += wv * s[0]; acc[4 * b4 + 1] += wv * s[1]; acc[4 * b4 + 2] += wv * s[2]; acc[4 * b4 + 3] += wv * s[3]; }
;     }
.LBB0_436:
	global_load_dwordx4 v[176:179], v[18:19], off
	v_lshl_add_u64 v[208:209], v[18:19], 0, s[34:35]
	global_load_dwordx4 v[180:183], v[208:209], off
	v_lshl_add_u64 v[208:209], v[208:209], 0, s[34:35]
	global_load_dwordx4 v[184:187], v[208:209], off
	v_lshl_add_u64 v[208:209], v[208:209], 0, s[34:35]
	global_load_dwordx4 v[188:191], v[208:209], off
	v_lshl_add_u64 v[208:209], v[208:209], 0, s[34:35]
	global_load_dwordx4 v[192:195], v[208:209], off
	v_lshl_add_u64 v[208:209], v[208:209], 0, s[34:35]
	global_load_dwordx4 v[196:199], v[208:209], off
	v_lshl_add_u64 v[208:209], v[208:209], 0, s[34:35]
	global_load_dwordx4 v[200:203], v[208:209], off
	v_lshl_add_u64 v[208:209], v[208:209], 0, s[34:35]
	global_load_dwordx4 v[204:207], v[208:209], off
	v_add_u32_e32 v116, s31, v122
	ds_read_b128 v[128:131], v116
	ds_read_b128 v[132:135], v116 offset:16
	ds_read_b128 v[136:139], v116 offset:32
	ds_read_b128 v[140:143], v116 offset:48
	s_addk_i32 s31, 0x300
	s_cmpk_eq_i32 s31, 0x1800
	s_waitcnt vmcnt(7) lgkmcnt(3)
	v_pk_fma_f32 v[114:115], v[178:179], v[128:129], v[114:115] op_sel_hi:[1, 0, 1]
	v_pk_fma_f32 v[112:113], v[176:177], v[128:129], v[112:113] op_sel_hi:[1, 0, 1]
	v_pk_fma_f32 v[110:111], v[178:179], v[128:129], v[110:111] op_sel:[0, 1, 0]
	v_pk_fma_f32 v[108:109], v[176:177], v[128:129], v[108:109] op_sel:[0, 1, 0]
	v_mov_b32_e32 v128, v131
	v_pk_fma_f32 v[102:103], v[178:179], v[128:129], v[102:103] op_sel_hi:[1, 0, 1]
	v_pk_fma_f32 v[100:101], v[176:177], v[128:129], v[100:101] op_sel_hi:[1, 0, 1]
	s_waitcnt lgkmcnt(2)
	v_mov_b32_e32 v128, v135
	v_pk_fma_f32 v[86:87], v[178:179], v[128:129], v[86:87] op_sel_hi:[1, 0, 1]
	v_pk_fma_f32 v[84:85], v[176:177], v[128:129], v[84:85] op_sel_hi:[1, 0, 1]
	s_waitcnt lgkmcnt(1)
	v_mov_b32_e32 v128, v139
	v_pk_fma_f32 v[70:71], v[178:179], v[128:129], v[70:71] op_sel_hi:[1, 0, 1]
	v_pk_fma_f32 v[68:69], v[176:177], v[128:129], v[68:69] op_sel_hi:[1, 0, 1]
	s_waitcnt lgkmcnt(0)
	v_mov_b32_e32 v128, v143
	v_pk_fma_f32 v[106:107], v[178:179], v[130:131], v[106:107] op_sel_hi:[1, 0, 1]
	v_pk_fma_f32 v[104:105], v[176:177], v[130:131], v[104:105] op_sel_hi:[1, 0, 1]
	v_pk_fma_f32 v[54:55], v[178:179], v[128:129], v[54:55] op_sel_hi:[1, 0, 1]
	v_pk_fma_f32 v[52:53], v[176:177], v[128:129], v[52:53] op_sel_hi:[1, 0, 1]
	ds_read_b128 v[128:131], v116 offset:64
	v_pk_fma_f32 v[98:99], v[178:179], v[132:133], v[98:99] op_sel_hi:[1, 0, 1]
	v_pk_fma_f32 v[96:97], v[176:177], v[132:133], v[96:97] op_sel_hi:[1, 0, 1]
	v_pk_fma_f32 v[94:95], v[178:179], v[132:133], v[94:95] op_sel:[0, 1, 0]
	v_pk_fma_f32 v[92:93], v[176:177], v[132:133], v[92:93] op_sel:[0, 1, 0]
	s_waitcnt lgkmcnt(0)
	v_pk_fma_f32 v[50:51], v[178:179], v[128:129], v[50:51] op_sel_hi:[1, 0, 1]
	v_pk_fma_f32 v[48:49], v[176:177], v[128:129], v[48:49] op_sel_hi:[1, 0, 1]
	v_pk_fma_f32 v[46:47], v[178:179], v[128:129], v[46:47] op_sel:[0, 1, 0]
	v_pk_fma_f32 v[44:45], v[176:177], v[128:129], v[44:45] op_sel:[0, 1, 0]
	v_mov_b32_e32 v128, v131
	v_pk_fma_f32 v[42:43], v[178:179], v[130:131], v[42:43] op_sel_hi:[1, 0, 1]
	v_pk_fma_f32 v[40:41], v[176:177], v[130:131], v[40:41] op_sel_hi:[1, 0, 1]
	v_pk_fma_f32 v[38:39], v[178:179], v[128:129], v[38:39] op_sel_hi:[1, 0, 1]
	v_pk_fma_f32 v[36:37], v[176:177], v[128:129], v[36:37] op_sel_hi:[1, 0, 1]
	ds_read_b128 v[128:131], v116 offset:80
	v_lshl_add_u64 v[132:133], v[18:19], 0, s[34:35]
	v_pk_fma_f32 v[90:91], v[178:179], v[134:135], v[90:91] op_sel_hi:[1, 0, 1]
	v_pk_fma_f32 v[88:89], v[176:177], v[134:135], v[88:89] op_sel_hi:[1, 0, 1]
	v_pk_fma_f32 v[82:83], v[178:179], v[136:137], v[82:83] op_sel_hi:[1, 0, 1]
	s_waitcnt lgkmcnt(0)
	v_pk_fma_f32 v[34:35], v[178:179], v[128:129], v[34:35] op_sel_hi:[1, 0, 1]
	v_pk_fma_f32 v[32:33], v[176:177], v[128:129], v[32:33] op_sel_hi:[1, 0, 1]
	v_pk_fma_f32 v[30:31], v[178:179], v[128:129], v[30:31] op_sel:[0, 1, 0]
	v_pk_fma_f32 v[28:29], v[176:177], v[128:129], v[28:29] op_sel:[0, 1, 0]
	v_mov_b32_e32 v128, v131
	v_pk_fma_f32 v[80:81], v[176:177], v[136:137], v[80:81] op_sel_hi:[1, 0, 1]
	v_pk_fma_f32 v[78:79], v[178:179], v[136:137], v[78:79] op_sel:[0, 1, 0]
	v_pk_fma_f32 v[76:77], v[176:177], v[136:137], v[76:77] op_sel:[0, 1, 0]
	v_pk_fma_f32 v[74:75], v[178:179], v[138:139], v[74:75] op_sel_hi:[1, 0, 1]
	v_pk_fma_f32 v[72:73], v[176:177], v[138:139], v[72:73] op_sel_hi:[1, 0, 1]
	v_pk_fma_f32 v[66:67], v[178:179], v[140:141], v[66:67] op_sel_hi:[1, 0, 1]
	v_pk_fma_f32 v[64:65], v[176:177], v[140:141], v[64:65] op_sel_hi:[1, 0, 1]
	v_pk_fma_f32 v[62:63], v[178:179], v[140:141], v[62:63] op_sel:[0, 1, 0]
	v_pk_fma_f32 v[60:61], v[176:177], v[140:141], v[60:61] op_sel:[0, 1, 0]
	v_pk_fma_f32 v[58:59], v[178:179], v[142:143], v[58:59] op_sel_hi:[1, 0, 1]
	v_pk_fma_f32 v[56:57], v[176:177], v[142:143], v[56:57] op_sel_hi:[1, 0, 1]
	v_pk_fma_f32 v[26:27], v[178:179], v[130:131], v[26:27] op_sel_hi:[1, 0, 1]
	v_pk_fma_f32 v[24:25], v[176:177], v[130:131], v[24:25] op_sel_hi:[1, 0, 1]
	v_pk_fma_f32 v[22:23], v[178:179], v[128:129], v[22:23] op_sel_hi:[1, 0, 1]
	v_pk_fma_f32 v[20:21], v[176:177], v[128:129], v[20:21] op_sel_hi:[1, 0, 1]
	ds_read_b128 v[128:131], v116 offset:96
	v_lshl_add_u64 v[18:19], v[18:19], 0, s[22:23]
	s_waitcnt vmcnt(6) lgkmcnt(0)
	v_pk_fma_f32 v[114:115], v[182:183], v[128:129], v[114:115] op_sel_hi:[1, 0, 1]
	v_pk_fma_f32 v[112:113], v[180:181], v[128:129], v[112:113] op_sel_hi:[1, 0, 1]
	v_pk_fma_f32 v[110:111], v[182:183], v[128:129], v[110:111] op_sel:[0, 1, 0]
	v_pk_fma_f32 v[108:109], v[180:181], v[128:129], v[108:109] op_sel:[0, 1, 0]
	v_mov_b32_e32 v128, v131
	v_pk_fma_f32 v[106:107], v[182:183], v[130:131], v[106:107] op_sel_hi:[1, 0, 1]
	v_pk_fma_f32 v[104:105], v[180:181], v[130:131], v[104:105] op_sel_hi:[1, 0, 1]
	v_pk_fma_f32 v[130:131], v[182:183], v[128:129], v[102:103] op_sel_hi:[1, 0, 1]
	v_pk_fma_f32 v[128:129], v[180:181], v[128:129], v[100:101] op_sel_hi:[1, 0, 1]
	ds_read_b128 v[100:103], v116 offset:112
	s_waitcnt lgkmcnt(0)
; #define LAS __attribute__((address_space(3)))
; __device__ __forceinline__ void gemv24_item(const float* W, int N, int j0, LAS float* sc, LAS float* red, float (&res)[6], const int tid) {
;     ...
;     for (int kk = 0; kk < 64; ++kk) {
;         const f32x4 wv = *(const f32x4*)(w + (size_t)kk * N);
;         const LAS f32x4* s4 = (const LAS f32x4*)(sc + (ks * 64 + kk) * 24);
; #pragma unroll
;         for (int b4 = 0; b4 < 6; ++b4) { const f32x4 s = s4[b4]; acc[4 * b4] += wv * s[0]; acc[4 * b4 + 1] += wv * s[1]; acc[4 * b4 + 2] += wv * s[2]; acc[4 * b4 + 3] += wv * s[3]; }
;     }
	v_pk_fma_f32 v[98:99], v[182:183], v[100:101], v[98:99] op_sel_hi:[1, 0, 1]
	v_pk_fma_f32 v[96:97], v[180:181], v[100:101], v[96:97] op_sel_hi:[1, 0, 1]
	v_pk_fma_f32 v[94:95], v[182:183], v[100:101], v[94:95] op_sel:[0, 1, 0]
	v_pk_fma_f32 v[92:93], v[180:181], v[100:101], v[92:93] op_sel:[0, 1, 0]
	v_mov_b32_e32 v100, v103
	v_pk_fma_f32 v[90:91], v[182:183], v[102:103], v[90:91] op_sel_hi:[1, 0, 1]
	v_pk_fma_f32 v[88:89], v[180:181], v[102:103], v[88:89] op_sel_hi:[1, 0, 1]
	v_pk_fma_f32 v[102:103], v[182:183], v[100:101], v[86:87] op_sel_hi:[1, 0, 1]
	v_pk_fma_f32 v[100:101], v[180:181], v[100:101], v[84:85] op_sel_hi:[1, 0, 1]
	ds_read_b128 v[84:87], v116 offset:128
	s_waitcnt lgkmcnt(0)
	v_pk_fma_f32 v[82:83], v[182:183], v[84:85], v[82:83] op_sel_hi:[1, 0, 1]
	v_pk_fma_f32 v[80:81], v[180:181], v[84:85], v[80:81] op_sel_hi:[1, 0, 1]
	v_pk_fma_f32 v[78:79], v[182:183], v[84:85], v[78:79] op_sel:[0, 1, 0]
	v_pk_fma_f32 v[76:77], v[180:181], v[84:85], v[76:77] op_sel:[0, 1, 0]
	v_mov_b32_e32 v84, v87
	v_pk_fma_f32 v[74:75], v[182:183], v[86:87], v[74:75] op_sel_hi:[1, 0, 1]
	v_pk_fma_f32 v[72:73], v[180:181], v[86:87], v[72:73] op_sel_hi:[1, 0, 1]
	v_pk_fma_f32 v[86:87], v[182:183], v[84:85], v[70:71] op_sel_hi:[1, 0, 1]
	v_pk_fma_f32 v[84:85], v[180:181], v[84:85], v[68:69] op_sel_hi:[1, 0, 1]
	ds_read_b128 v[68:71], v116 offset:144
	s_waitcnt lgkmcnt(0)
	v_pk_fma_f32 v[66:67], v[182:183], v[68:69], v[66:67] op_sel_hi:[1, 0, 1]
	v_pk_fma_f32 v[64:65], v[180:181], v[68:69], v[64:65] op_sel_hi:[1, 0, 1]
	v_pk_fma_f32 v[62:63], v[182:183], v[68:69], v[62:63] op_sel:[0, 1, 0]
	v_pk_fma_f32 v[60:61], v[180:181], v[68:69], v[60:61] op_sel:[0, 1, 0]
	v_mov_b32_e32 v68, v71
	v_pk_fma_f32 v[58:59], v[182:183], v[70:71], v[58:59] op_sel_hi:[1, 0, 1]
	v_pk_fma_f32 v[56:57], v[180:181], v[70:71], v[56:57] op_sel_hi:[1, 0, 1]
	v_pk_fma_f32 v[70:71], v[182:183], v[68:69], v[54:55] op_sel_hi:[1, 0, 1]
	v_pk_fma_f32 v[68:69], v[180:181], v[68:69], v[52:53] op_sel_hi:[1, 0, 1]
	ds_read_b128 v[52:55], v116 offset:160
	s_waitcnt lgkmcnt(0)
	v_pk_fma_f32 v[50:51], v[182:183], v[52:53], v[50:51] op_sel_hi:[1, 0, 1]
	v_pk_fma_f32 v[48:49], v[180:181], v[52:53], v[48:49] op_sel_hi:[1, 0, 1]
	v_pk_fma_f32 v[46:47], v[182:183], v[52:53], v[46:47] op_sel:[0, 1, 0]
	v_pk_fma_f32 v[44:45], v[180:181], v[52:53], v[44:45] op_sel:[0, 1, 0]
	v_mov_b32_e32 v52, v55
	v_pk_fma_f32 v[42:43], v[182:183], v[54:55], v[42:43] op_sel_hi:[1, 0, 1]
	v_pk_fma_f32 v[40:41], v[180:181], v[54:55], v[40:41] op_sel_hi:[1, 0, 1]
	v_pk_fma_f32 v[54:55], v[182:183], v[52:53], v[38:39] op_sel_hi:[1, 0, 1]
	v_pk_fma_f32 v[52:53], v[180:181], v[52:53], v[36:37] op_sel_hi:[1, 0, 1]
	ds_read_b128 v[36:39], v116 offset:176
	s_waitcnt lgkmcnt(0)
	v_pk_fma_f32 v[134:135], v[180:181], v[38:39], v[24:25] op_sel_hi:[1, 0, 1]
	v_mov_b32_e32 v24, v39
	v_pk_fma_f32 v[34:35], v[182:183], v[36:37], v[34:35] op_sel_hi:[1, 0, 1]
	v_pk_fma_f32 v[32:33], v[180:181], v[36:37], v[32:33] op_sel_hi:[1, 0, 1]
	v_pk_fma_f32 v[30:31], v[182:183], v[36:37], v[30:31] op_sel:[0, 1, 0]
	v_pk_fma_f32 v[28:29], v[180:181], v[36:37], v[28:29] op_sel:[0, 1, 0]
	v_pk_fma_f32 v[36:37], v[182:183], v[38:39], v[26:27] op_sel_hi:[1, 0, 1]
	v_pk_fma_f32 v[38:39], v[182:183], v[24:25], v[22:23] op_sel_hi:[1, 0, 1]
	v_lshl_add_u64 v[126:127], v[132:133], 0, s[34:35]
	v_pk_fma_f32 v[124:125], v[180:181], v[24:25], v[20:21] op_sel_hi:[1, 0, 1]
	ds_read_b128 v[24:27], v116 offset:192
	v_lshl_add_u64 v[126:127], v[126:127], 0, s[34:35]
	s_waitcnt vmcnt(5) lgkmcnt(0)
	v_pk_fma_f32 v[114:115], v[186:187], v[24:25], v[114:115] op_sel_hi:[1, 0, 1]
	v_pk_fma_f32 v[112:113], v[184:185], v[24:25], v[112:113] op_sel_hi:[1, 0, 1]
	v_pk_fma_f32 v[110:111], v[186:187], v[24:25], v[110:111] op_sel:[0, 1, 0]
	v_pk_fma_f32 v[108:109], v[184:185], v[24:25], v[108:109] op_sel:[0, 1, 0]
	v_mov_b32_e32 v24, v27
	v_pk_fma_f32 v[106:107], v[186:187], v[26:27], v[106:107] op_sel_hi:[1, 0, 1]
	v_pk_fma_f32 v[104:105], v[184:185], v[26:27], v[104:105] op_sel_hi:[1, 0, 1]
	v_pk_fma_f32 v[130:131], v[186:187], v[24:25], v[130:131] op_sel_hi:[1, 0, 1]
	v_pk_fma_f32 v[128:129], v[184:185], v[24:25], v[128:129] op_sel_hi:[1, 0, 1]
	ds_read_b128 v[24:27], v116 offset:208
	s_waitcnt lgkmcnt(0)
	v_pk_fma_f32 v[98:99], v[186:187], v[24:25], v[98:99] op_sel_hi:[1, 0, 1]
	v_pk_fma_f32 v[96:97], v[184:185], v[24:25], v[96:97] op_sel_hi:[1, 0, 1]
	v_pk_fma_f32 v[94:95], v[186:187], v[24:25], v[94:95] op_sel:[0, 1, 0]
	v_pk_fma_f32 v[92:93], v[184:185], v[24:25], v[92:93] op_sel:[0, 1, 0]
	v_mov_b32_e32 v24, v27
	v_pk_fma_f32 v[90:91], v[186:187], v[26:27], v[90:91] op_sel_hi:[1, 0, 1]
	v_pk_fma_f32 v[88:89], v[184:185], v[26:27], v[88:89] op_sel_hi:[1, 0, 1]
	v_pk_fma_f32 v[102:103], v[186:187], v[24:25], v[102:103] op_sel_hi:[1, 0, 1]
	v_pk_fma_f32 v[100:101], v[184:185], v[24:25], v[100:101] op_sel_hi:[1, 0, 1]
	ds_read_b128 v[24:27], v116 offset:224
	s_waitcnt lgkmcnt(0)
	v_pk_fma_f32 v[82:83], v[186:187], v[24:25], v[82:83] op_sel_hi:[1, 0, 1]
	v_pk_fma_f32 v[80:81], v[184:185], v[24:25], v[80:81] op_sel_hi:[1, 0, 1]
	v_pk_fma_f32 v[78:79], v[186:187], v[24:25], v[78:79] op_sel:[0, 1, 0]
	v_pk_fma_f32 v[76:77], v[184:185], v[24:25], v[76:77] op_sel:[0, 1, 0]
	v_mov_b32_e32 v24, v27
	v_pk_fma_f32 v[74:75], v[186:187], v[26:27], v[74:75] op_sel_hi:[1, 0, 1]
	v_pk_fma_f32 v[72:73], v[184:185], v[26:27], v[72:73] op_sel_hi:[1, 0, 1]
	v_pk_fma_f32 v[86:87], v[186:187], v[24:25], v[86:87] op_sel_hi:[1, 0, 1]
	v_pk_fma_f32 v[84:85], v[184:185], v[24:25], v[84:85] op_sel_hi:[1, 0, 1]
	ds_read_b128 v[24:27], v116 offset:240
	s_waitcnt lgkmcnt(0)
; #define LAS __attribute__((address_space(3)))
; __device__ __forceinline__ void gemv24_item(const float* W, int N, int j0, LAS float* sc, LAS float* red, float (&res)[6], const int tid) {
;     ...
;     for (int kk = 0; kk < 64; ++kk) {
;         const f32x4 wv = *(const f32x4*)(w + (size_t)kk * N);
;         const LAS f32x4* s4 = (const LAS f32x4*)(sc + (ks * 64 + kk) * 24);
; #pragma unroll
;         for (int b4 = 0; b4 < 6; ++b4) { const f32x4 s = s4[b4]; acc[4 * b4] += wv * s[0]; acc[4 * b4 + 1] += wv * s[1]; acc[4 * b4 + 2] += wv * s[2]; acc[4 * b4 + 3] += wv * s[3]; }
;     }
	v_pk_fma_f32 v[66:67], v[186:187], v[24:25], v[66:67] op_sel_hi:[1, 0, 1]
	v_pk_fma_f32 v[64:65], v[184:185], v[24:25], v[64:65] op_sel_hi:[1, 0, 1]
	v_pk_fma_f32 v[62:63], v[186:187], v[24:25], v[62:63] op_sel:[0, 1, 0]
	v_pk_fma_f32 v[60:61], v[184:185], v[24:25], v[60:61] op_sel:[0, 1, 0]
	v_mov_b32_e32 v24, v27
	v_pk_fma_f32 v[58:59], v[186:187], v[26:27], v[58:59] op_sel_hi:[1, 0, 1]
	v_pk_fma_f32 v[56:57], v[184:185], v[26:27], v[56:57] op_sel_hi:[1, 0, 1]
	v_pk_fma_f32 v[70:71], v[186:187], v[24:25], v[70:71] op_sel_hi:[1, 0, 1]
	v_pk_fma_f32 v[68:69], v[184:185], v[24:25], v[68:69] op_sel_hi:[1, 0, 1]
	ds_read_b128 v[24:27], v116 offset:256
	s_waitcnt lgkmcnt(0)
	v_pk_fma_f32 v[50:51], v[186:187], v[24:25], v[50:51] op_sel_hi:[1, 0, 1]
	v_pk_fma_f32 v[48:49], v[184:185], v[24:25], v[48:49] op_sel_hi:[1, 0, 1]
	v_pk_fma_f32 v[46:47], v[186:187], v[24:25], v[46:47] op_sel:[0, 1, 0]
	v_pk_fma_f32 v[44:45], v[184:185], v[24:25], v[44:45] op_sel:[0, 1, 0]
	v_mov_b32_e32 v24, v27
	v_pk_fma_f32 v[42:43], v[186:187], v[26:27], v[42:43] op_sel_hi:[1, 0, 1]
	v_pk_fma_f32 v[40:41], v[184:185], v[26:27], v[40:41] op_sel_hi:[1, 0, 1]
	v_pk_fma_f32 v[54:55], v[186:187], v[24:25], v[54:55] op_sel_hi:[1, 0, 1]
	v_pk_fma_f32 v[52:53], v[184:185], v[24:25], v[52:53] op_sel_hi:[1, 0, 1]
	ds_read_b128 v[24:27], v116 offset:272
	s_waitcnt lgkmcnt(0)
	v_pk_fma_f32 v[34:35], v[186:187], v[24:25], v[34:35] op_sel_hi:[1, 0, 1]
	v_pk_fma_f32 v[32:33], v[184:185], v[24:25], v[32:33] op_sel_hi:[1, 0, 1]
	v_pk_fma_f32 v[30:31], v[186:187], v[24:25], v[30:31] op_sel:[0, 1, 0]
	v_pk_fma_f32 v[28:29], v[184:185], v[24:25], v[28:29] op_sel:[0, 1, 0]
	v_mov_b32_e32 v24, v27
	v_pk_fma_f32 v[36:37], v[186:187], v[26:27], v[36:37] op_sel_hi:[1, 0, 1]
	v_pk_fma_f32 v[132:133], v[184:185], v[26:27], v[134:135] op_sel_hi:[1, 0, 1]
	v_pk_fma_f32 v[38:39], v[186:187], v[24:25], v[38:39] op_sel_hi:[1, 0, 1]
	v_pk_fma_f32 v[124:125], v[184:185], v[24:25], v[124:125] op_sel_hi:[1, 0, 1]
	ds_read_b128 v[24:27], v116 offset:288
	v_lshl_add_u64 v[126:127], v[126:127], 0, s[34:35]
	s_waitcnt vmcnt(4) lgkmcnt(0)
	v_pk_fma_f32 v[114:115], v[190:191], v[24:25], v[114:115] op_sel_hi:[1, 0, 1]
	v_pk_fma_f32 v[112:113], v[188:189], v[24:25], v[112:113] op_sel_hi:[1, 0, 1]
	v_pk_fma_f32 v[110:111], v[190:191], v[24:25], v[110:111] op_sel:[0, 1, 0]
	v_pk_fma_f32 v[108:109], v[188:189], v[24:25], v[108:109] op_sel:[0, 1, 0]
	v_mov_b32_e32 v24, v27
	v_pk_fma_f32 v[106:107], v[190:191], v[26:27], v[106:107] op_sel_hi:[1, 0, 1]
	v_pk_fma_f32 v[104:105], v[188:189], v[26:27], v[104:105] op_sel_hi:[1, 0, 1]
	v_pk_fma_f32 v[130:131], v[190:191], v[24:25], v[130:131] op_sel_hi:[1, 0, 1]
	v_pk_fma_f32 v[128:129], v[188:189], v[24:25], v[128:129] op_sel_hi:[1, 0, 1]
	ds_read_b128 v[24:27], v116 offset:304
	s_waitcnt lgkmcnt(0)
	v_pk_fma_f32 v[98:99], v[190:191], v[24:25], v[98:99] op_sel_hi:[1, 0, 1]
	v_pk_fma_f32 v[96:97], v[188:189], v[24:25], v[96:97] op_sel_hi:[1, 0, 1]
	v_pk_fma_f32 v[94:95], v[190:191], v[24:25], v[94:95] op_sel:[0, 1, 0]
	v_pk_fma_f32 v[92:93], v[188:189], v[24:25], v[92:93] op_sel:[0, 1, 0]
	v_mov_b32_e32 v24, v27
	v_pk_fma_f32 v[90:91], v[190:191], v[26:27], v[90:91] op_sel_hi:[1, 0, 1]
	v_pk_fma_f32 v[88:89], v[188:189], v[26:27], v[88:89] op_sel_hi:[1, 0, 1]
	v_pk_fma_f32 v[102:103], v[190:191], v[24:25], v[102:103] op_sel_hi:[1, 0, 1]
	v_pk_fma_f32 v[100:101], v[188:189], v[24:25], v[100:101] op_sel_hi:[1, 0, 1]
	ds_read_b128 v[24:27], v116 offset:320
	s_waitcnt lgkmcnt(0)
	v_pk_fma_f32 v[82:83], v[190:191], v[24:25], v[82:83] op_sel_hi:[1, 0, 1]
	v_pk_fma_f32 v[80:81], v[188:189], v[24:25], v[80:81] op_sel_hi:[1, 0, 1]
	v_pk_fma_f32 v[78:79], v[190:191], v[24:25], v[78:79] op_sel:[0, 1, 0]
	v_pk_fma_f32 v[76:77], v[188:189], v[24:25], v[76:77] op_sel:[0, 1, 0]
	v_mov_b32_e32 v24, v27
	v_pk_fma_f32 v[74:75], v[190:191], v[26:27], v[74:75] op_sel_hi:[1, 0, 1]
	v_pk_fma_f32 v[72:73], v[188:189], v[26:27], v[72:73] op_sel_hi:[1, 0, 1]
	v_pk_fma_f32 v[86:87], v[190:191], v[24:25], v[86:87] op_sel_hi:[1, 0, 1]
	v_pk_fma_f32 v[84:85], v[188:189], v[24:25], v[84:85] op_sel_hi:[1, 0, 1]
	ds_read_b128 v[24:27], v116 offset:336
	s_waitcnt lgkmcnt(0)
	v_pk_fma_f32 v[66:67], v[190:191], v[24:25], v[66:67] op_sel_hi:[1, 0, 1]
	v_pk_fma_f32 v[64:65], v[188:189], v[24:25], v[64:65] op_sel_hi:[1, 0, 1]
	v_pk_fma_f32 v[62:63], v[190:191], v[24:25], v[62:63] op_sel:[0, 1, 0]
	v_pk_fma_f32 v[60:61], v[188:189], v[24:25], v[60:61] op_sel:[0, 1, 0]
	v_mov_b32_e32 v24, v27
	v_pk_fma_f32 v[58:59], v[190:191], v[26:27], v[58:59] op_sel_hi:[1, 0, 1]
	v_pk_fma_f32 v[56:57], v[188:189], v[26:27], v[56:57] op_sel_hi:[1, 0, 1]
	v_pk_fma_f32 v[70:71], v[190:191], v[24:25], v[70:71] op_sel_hi:[1, 0, 1]
	v_pk_fma_f32 v[68:69], v[188:189], v[24:25], v[68:69] op_sel_hi:[1, 0, 1]
	ds_read_b128 v[24:27], v116 offset:352
	s_waitcnt lgkmcnt(0)
	v_pk_fma_f32 v[50:51], v[190:191], v[24:25], v[50:51] op_sel_hi:[1, 0, 1]
	v_pk_fma_f32 v[48:49], v[188:189], v[24:25], v[48:49] op_sel_hi:[1, 0, 1]
	v_pk_fma_f32 v[46:47], v[190:191], v[24:25], v[46:47] op_sel:[0, 1, 0]
	v_pk_fma_f32 v[44:45], v[188:189], v[24:25], v[44:45] op_sel:[0, 1, 0]
	v_mov_b32_e32 v24, v27
	v_pk_fma_f32 v[42:43], v[190:191], v[26:27], v[42:43] op_sel_hi:[1, 0, 1]
	v_pk_fma_f32 v[40:41], v[188:189], v[26:27], v[40:41] op_sel_hi:[1, 0, 1]
	v_pk_fma_f32 v[54:55], v[190:191], v[24:25], v[54:55] op_sel_hi:[1, 0, 1]
	v_pk_fma_f32 v[52:53], v[188:189], v[24:25], v[52:53] op_sel_hi:[1, 0, 1]
	ds_read_b128 v[24:27], v116 offset:368
	s_waitcnt lgkmcnt(0)
; #define LAS __attribute__((address_space(3)))
; __device__ __forceinline__ void gemv24_item(const float* W, int N, int j0, LAS float* sc, LAS float* red, float (&res)[6], const int tid) {
;     ...
;     for (int kk = 0; kk < 64; ++kk) {
;         const f32x4 wv = *(const f32x4*)(w + (size_t)kk * N);
;         const LAS f32x4* s4 = (const LAS f32x4*)(sc + (ks * 64 + kk) * 24);
; #pragma unroll
;         for (int b4 = 0; b4 < 6; ++b4) { const f32x4 s = s4[b4]; acc[4 * b4] += wv * s[0]; acc[4 * b4 + 1] += wv * s[1]; acc[4 * b4 + 2] += wv * s[2]; acc[4 * b4 + 3] += wv * s[3]; }
;     }
	v_pk_fma_f32 v[34:35], v[190:191], v[24:25], v[34:35] op_sel_hi:[1, 0, 1]
	v_pk_fma_f32 v[32:33], v[188:189], v[24:25], v[32:33] op_sel_hi:[1, 0, 1]
	v_pk_fma_f32 v[30:31], v[190:191], v[24:25], v[30:31] op_sel:[0, 1, 0]
	v_pk_fma_f32 v[28:29], v[188:189], v[24:25], v[28:29] op_sel:[0, 1, 0]
	v_mov_b32_e32 v24, v27
	v_pk_fma_f32 v[36:37], v[190:191], v[26:27], v[36:37] op_sel_hi:[1, 0, 1]
	v_pk_fma_f32 v[132:133], v[188:189], v[26:27], v[132:133] op_sel_hi:[1, 0, 1]
	v_pk_fma_f32 v[38:39], v[190:191], v[24:25], v[38:39] op_sel_hi:[1, 0, 1]
	v_pk_fma_f32 v[124:125], v[188:189], v[24:25], v[124:125] op_sel_hi:[1, 0, 1]
	ds_read_b128 v[24:27], v116 offset:384
	v_lshl_add_u64 v[126:127], v[126:127], 0, s[34:35]
	s_waitcnt vmcnt(3) lgkmcnt(0)
	v_pk_fma_f32 v[114:115], v[194:195], v[24:25], v[114:115] op_sel_hi:[1, 0, 1]
	v_pk_fma_f32 v[112:113], v[192:193], v[24:25], v[112:113] op_sel_hi:[1, 0, 1]
	v_pk_fma_f32 v[110:111], v[194:195], v[24:25], v[110:111] op_sel:[0, 1, 0]
	v_pk_fma_f32 v[108:109], v[192:193], v[24:25], v[108:109] op_sel:[0, 1, 0]
	v_mov_b32_e32 v24, v27
	v_pk_fma_f32 v[106:107], v[194:195], v[26:27], v[106:107] op_sel_hi:[1, 0, 1]
	v_pk_fma_f32 v[104:105], v[192:193], v[26:27], v[104:105] op_sel_hi:[1, 0, 1]
	v_pk_fma_f32 v[130:131], v[194:195], v[24:25], v[130:131] op_sel_hi:[1, 0, 1]
	v_pk_fma_f32 v[128:129], v[192:193], v[24:25], v[128:129] op_sel_hi:[1, 0, 1]
	ds_read_b128 v[24:27], v116 offset:400
	s_waitcnt lgkmcnt(0)
	v_pk_fma_f32 v[98:99], v[194:195], v[24:25], v[98:99] op_sel_hi:[1, 0, 1]
	v_pk_fma_f32 v[96:97], v[192:193], v[24:25], v[96:97] op_sel_hi:[1, 0, 1]
	v_pk_fma_f32 v[94:95], v[194:195], v[24:25], v[94:95] op_sel:[0, 1, 0]
	v_pk_fma_f32 v[92:93], v[192:193], v[24:25], v[92:93] op_sel:[0, 1, 0]
	v_mov_b32_e32 v24, v27
	v_pk_fma_f32 v[90:91], v[194:195], v[26:27], v[90:91] op_sel_hi:[1, 0, 1]
	v_pk_fma_f32 v[88:89], v[192:193], v[26:27], v[88:89] op_sel_hi:[1, 0, 1]
	v_pk_fma_f32 v[102:103], v[194:195], v[24:25], v[102:103] op_sel_hi:[1, 0, 1]
	v_pk_fma_f32 v[100:101], v[192:193], v[24:25], v[100:101] op_sel_hi:[1, 0, 1]
	ds_read_b128 v[24:27], v116 offset:416
	s_waitcnt lgkmcnt(0)
	v_pk_fma_f32 v[82:83], v[194:195], v[24:25], v[82:83] op_sel_hi:[1, 0, 1]
	v_pk_fma_f32 v[80:81], v[192:193], v[24:25], v[80:81] op_sel_hi:[1, 0, 1]
	v_pk_fma_f32 v[78:79], v[194:195], v[24:25], v[78:79] op_sel:[0, 1, 0]
	v_pk_fma_f32 v[76:77], v[192:193], v[24:25], v[76:77] op_sel:[0, 1, 0]
	v_mov_b32_e32 v24, v27
	v_pk_fma_f32 v[74:75], v[194:195], v[26:27], v[74:75] op_sel_hi:[1, 0, 1]
	v_pk_fma_f32 v[72:73], v[192:193], v[26:27], v[72:73] op_sel_hi:[1, 0, 1]
	v_pk_fma_f32 v[86:87], v[194:195], v[24:25], v[86:87] op_sel_hi:[1, 0, 1]
	v_pk_fma_f32 v[84:85], v[192:193], v[24:25], v[84:85] op_sel_hi:[1, 0, 1]
	ds_read_b128 v[24:27], v116 offset:432
	s_waitcnt lgkmcnt(0)
	v_pk_fma_f32 v[66:67], v[194:195], v[24:25], v[66:67] op_sel_hi:[1, 0, 1]
	v_pk_fma_f32 v[64:65], v[192:193], v[24:25], v[64:65] op_sel_hi:[1, 0, 1]
	v_pk_fma_f32 v[62:63], v[194:195], v[24:25], v[62:63] op_sel:[0, 1, 0]
	v_pk_fma_f32 v[60:61], v[192:193], v[24:25], v[60:61] op_sel:[0, 1, 0]
	v_mov_b32_e32 v24, v27
	v_pk_fma_f32 v[58:59], v[194:195], v[26:27], v[58:59] op_sel_hi:[1, 0, 1]
	v_pk_fma_f32 v[56:57], v[192:193], v[26:27], v[56:57] op_sel_hi:[1, 0, 1]
	v_pk_fma_f32 v[70:71], v[194:195], v[24:25], v[70:71] op_sel_hi:[1, 0, 1]
	v_pk_fma_f32 v[68:69], v[192:193], v[24:25], v[68:69] op_sel_hi:[1, 0, 1]
	ds_read_b128 v[24:27], v116 offset:448
	s_waitcnt lgkmcnt(0)
	v_pk_fma_f32 v[50:51], v[194:195], v[24:25], v[50:51] op_sel_hi:[1, 0, 1]
	v_pk_fma_f32 v[48:49], v[192:193], v[24:25], v[48:49] op_sel_hi:[1, 0, 1]
	v_pk_fma_f32 v[46:47], v[194:195], v[24:25], v[46:47] op_sel:[0, 1, 0]
	v_pk_fma_f32 v[44:45], v[192:193], v[24:25], v[44:45] op_sel:[0, 1, 0]
	v_mov_b32_e32 v24, v27
	v_pk_fma_f32 v[42:43], v[194:195], v[26:27], v[42:43] op_sel_hi:[1, 0, 1]
	v_pk_fma_f32 v[40:41], v[192:193], v[26:27], v[40:41] op_sel_hi:[1, 0, 1]
	v_pk_fma_f32 v[54:55], v[194:195], v[24:25], v[54:55] op_sel_hi:[1, 0, 1]
	v_pk_fma_f32 v[52:53], v[192:193], v[24:25], v[52:53] op_sel_hi:[1, 0, 1]
	ds_read_b128 v[24:27], v116 offset:464
	s_waitcnt lgkmcnt(0)
	v_pk_fma_f32 v[34:35], v[194:195], v[24:25], v[34:35] op_sel_hi:[1, 0, 1]
	v_pk_fma_f32 v[32:33], v[192:193], v[24:25], v[32:33] op_sel_hi:[1, 0, 1]
	v_pk_fma_f32 v[30:31], v[194:195], v[24:25], v[30:31] op_sel:[0, 1, 0]
	v_pk_fma_f32 v[28:29], v[192:193], v[24:25], v[28:29] op_sel:[0, 1, 0]
	v_mov_b32_e32 v24, v27
	v_pk_fma_f32 v[36:37], v[194:195], v[26:27], v[36:37] op_sel_hi:[1, 0, 1]
	v_pk_fma_f32 v[132:133], v[192:193], v[26:27], v[132:133] op_sel_hi:[1, 0, 1]
	v_pk_fma_f32 v[38:39], v[194:195], v[24:25], v[38:39] op_sel_hi:[1, 0, 1]
	v_pk_fma_f32 v[124:125], v[192:193], v[24:25], v[124:125] op_sel_hi:[1, 0, 1]
	ds_read_b128 v[24:27], v116 offset:480
	v_lshl_add_u64 v[126:127], v[126:127], 0, s[34:35]
	s_waitcnt vmcnt(2) lgkmcnt(0)
	v_pk_fma_f32 v[114:115], v[198:199], v[24:25], v[114:115] op_sel_hi:[1, 0, 1]
	v_pk_fma_f32 v[112:113], v[196:197], v[24:25], v[112:113] op_sel_hi:[1, 0, 1]
	v_pk_fma_f32 v[110:111], v[198:199], v[24:25], v[110:111] op_sel:[0, 1, 0]
	v_pk_fma_f32 v[108:109], v[196:197], v[24:25], v[108:109] op_sel:[0, 1, 0]
	v_mov_b32_e32 v24, v27
	v_pk_fma_f32 v[106:107], v[198:199], v[26:27], v[106:107] op_sel_hi:[1, 0, 1]
	v_pk_fma_f32 v[104:105], v[196:197], v[26:27], v[104:105] op_sel_hi:[1, 0, 1]
	v_pk_fma_f32 v[130:131], v[198:199], v[24:25], v[130:131] op_sel_hi:[1, 0, 1]
	v_pk_fma_f32 v[128:129], v[196:197], v[24:25], v[128:129] op_sel_hi:[1, 0, 1]
	ds_read_b128 v[24:27], v116 offset:496
	s_waitcnt lgkmcnt(0)
; #define LAS __attribute__((address_space(3)))
; __device__ __forceinline__ void gemv24_item(const float* W, int N, int j0, LAS float* sc, LAS float* red, float (&res)[6], const int tid) {
;     ...
;     for (int kk = 0; kk < 64; ++kk) {
;         const f32x4 wv = *(const f32x4*)(w + (size_t)kk * N);
;         const LAS f32x4* s4 = (const LAS f32x4*)(sc + (ks * 64 + kk) * 24);
; #pragma unroll
;         for (int b4 = 0; b4 < 6; ++b4) { const f32x4 s = s4[b4]; acc[4 * b4] += wv * s[0]; acc[4 * b4 + 1] += wv * s[1]; acc[4 * b4 + 2] += wv * s[2]; acc[4 * b4 + 3] += wv * s[3]; }
;     }
	v_pk_fma_f32 v[98:99], v[198:199], v[24:25], v[98:99] op_sel_hi:[1, 0, 1]
	v_pk_fma_f32 v[96:97], v[196:197], v[24:25], v[96:97] op_sel_hi:[1, 0, 1]
	v_pk_fma_f32 v[94:95], v[198:199], v[24:25], v[94:95] op_sel:[0, 1, 0]
	v_pk_fma_f32 v[92:93], v[196:197], v[24:25], v[92:93] op_sel:[0, 1, 0]
	v_mov_b32_e32 v24, v27
	v_pk_fma_f32 v[90:91], v[198:199], v[26:27], v[90:91] op_sel_hi:[1, 0, 1]
	v_pk_fma_f32 v[88:89], v[196:197], v[26:27], v[88:89] op_sel_hi:[1, 0, 1]
	v_pk_fma_f32 v[102:103], v[198:199], v[24:25], v[102:103] op_sel_hi:[1, 0, 1]
	v_pk_fma_f32 v[100:101], v[196:197], v[24:25], v[100:101] op_sel_hi:[1, 0, 1]
	ds_read_b128 v[24:27], v116 offset:512
	s_waitcnt lgkmcnt(0)
	v_pk_fma_f32 v[82:83], v[198:199], v[24:25], v[82:83] op_sel_hi:[1, 0, 1]
	v_pk_fma_f32 v[80:81], v[196:197], v[24:25], v[80:81] op_sel_hi:[1, 0, 1]
	v_pk_fma_f32 v[78:79], v[198:199], v[24:25], v[78:79] op_sel:[0, 1, 0]
	v_pk_fma_f32 v[76:77], v[196:197], v[24:25], v[76:77] op_sel:[0, 1, 0]
	v_mov_b32_e32 v24, v27
	v_pk_fma_f32 v[74:75], v[198:199], v[26:27], v[74:75] op_sel_hi:[1, 0, 1]
	v_pk_fma_f32 v[72:73], v[196:197], v[26:27], v[72:73] op_sel_hi:[1, 0, 1]
	v_pk_fma_f32 v[86:87], v[198:199], v[24:25], v[86:87] op_sel_hi:[1, 0, 1]
	v_pk_fma_f32 v[84:85], v[196:197], v[24:25], v[84:85] op_sel_hi:[1, 0, 1]
	ds_read_b128 v[24:27], v116 offset:528
	s_waitcnt lgkmcnt(0)
	v_pk_fma_f32 v[66:67], v[198:199], v[24:25], v[66:67] op_sel_hi:[1, 0, 1]
	v_pk_fma_f32 v[64:65], v[196:197], v[24:25], v[64:65] op_sel_hi:[1, 0, 1]
	v_pk_fma_f32 v[62:63], v[198:199], v[24:25], v[62:63] op_sel:[0, 1, 0]
	v_pk_fma_f32 v[60:61], v[196:197], v[24:25], v[60:61] op_sel:[0, 1, 0]
	v_mov_b32_e32 v24, v27
	v_pk_fma_f32 v[58:59], v[198:199], v[26:27], v[58:59] op_sel_hi:[1, 0, 1]
	v_pk_fma_f32 v[56:57], v[196:197], v[26:27], v[56:57] op_sel_hi:[1, 0, 1]
	v_pk_fma_f32 v[70:71], v[198:199], v[24:25], v[70:71] op_sel_hi:[1, 0, 1]
	v_pk_fma_f32 v[68:69], v[196:197], v[24:25], v[68:69] op_sel_hi:[1, 0, 1]
	ds_read_b128 v[24:27], v116 offset:544
	s_waitcnt lgkmcnt(0)
	v_pk_fma_f32 v[50:51], v[198:199], v[24:25], v[50:51] op_sel_hi:[1, 0, 1]
	v_pk_fma_f32 v[48:49], v[196:197], v[24:25], v[48:49] op_sel_hi:[1, 0, 1]
	v_pk_fma_f32 v[46:47], v[198:199], v[24:25], v[46:47] op_sel:[0, 1, 0]
	v_pk_fma_f32 v[44:45], v[196:197], v[24:25], v[44:45] op_sel:[0, 1, 0]
	v_mov_b32_e32 v24, v27
	v_pk_fma_f32 v[42:43], v[198:199], v[26:27], v[42:43] op_sel_hi:[1, 0, 1]
	v_pk_fma_f32 v[40:41], v[196:197], v[26:27], v[40:41] op_sel_hi:[1, 0, 1]
	v_pk_fma_f32 v[54:55], v[198:199], v[24:25], v[54:55] op_sel_hi:[1, 0, 1]
	v_pk_fma_f32 v[52:53], v[196:197], v[24:25], v[52:53] op_sel_hi:[1, 0, 1]
	ds_read_b128 v[24:27], v116 offset:560
	s_waitcnt lgkmcnt(0)
	v_pk_fma_f32 v[34:35], v[198:199], v[24:25], v[34:35] op_sel_hi:[1, 0, 1]
	v_pk_fma_f32 v[32:33], v[196:197], v[24:25], v[32:33] op_sel_hi:[1, 0, 1]
	v_pk_fma_f32 v[30:31], v[198:199], v[24:25], v[30:31] op_sel:[0, 1, 0]
	v_pk_fma_f32 v[28:29], v[196:197], v[24:25], v[28:29] op_sel:[0, 1, 0]
	v_mov_b32_e32 v24, v27
	v_pk_fma_f32 v[36:37], v[198:199], v[26:27], v[36:37] op_sel_hi:[1, 0, 1]
	v_pk_fma_f32 v[132:133], v[196:197], v[26:27], v[132:133] op_sel_hi:[1, 0, 1]
	v_pk_fma_f32 v[38:39], v[198:199], v[24:25], v[38:39] op_sel_hi:[1, 0, 1]
	v_pk_fma_f32 v[124:125], v[196:197], v[24:25], v[124:125] op_sel_hi:[1, 0, 1]
	ds_read_b128 v[24:27], v116 offset:576
	s_waitcnt vmcnt(1) lgkmcnt(0)
	v_pk_fma_f32 v[114:115], v[202:203], v[24:25], v[114:115] op_sel_hi:[1, 0, 1]
	v_pk_fma_f32 v[112:113], v[200:201], v[24:25], v[112:113] op_sel_hi:[1, 0, 1]
	v_pk_fma_f32 v[110:111], v[202:203], v[24:25], v[110:111] op_sel:[0, 1, 0]
	v_pk_fma_f32 v[108:109], v[200:201], v[24:25], v[108:109] op_sel:[0, 1, 0]
	v_mov_b32_e32 v24, v27
	v_pk_fma_f32 v[106:107], v[202:203], v[26:27], v[106:107] op_sel_hi:[1, 0, 1]
	v_pk_fma_f32 v[104:105], v[200:201], v[26:27], v[104:105] op_sel_hi:[1, 0, 1]
	v_pk_fma_f32 v[130:131], v[202:203], v[24:25], v[130:131] op_sel_hi:[1, 0, 1]
	v_pk_fma_f32 v[128:129], v[200:201], v[24:25], v[128:129] op_sel_hi:[1, 0, 1]
	ds_read_b128 v[24:27], v116 offset:592
	s_waitcnt lgkmcnt(0)
	v_pk_fma_f32 v[98:99], v[202:203], v[24:25], v[98:99] op_sel_hi:[1, 0, 1]
	v_pk_fma_f32 v[96:97], v[200:201], v[24:25], v[96:97] op_sel_hi:[1, 0, 1]
	v_pk_fma_f32 v[94:95], v[202:203], v[24:25], v[94:95] op_sel:[0, 1, 0]
	v_pk_fma_f32 v[92:93], v[200:201], v[24:25], v[92:93] op_sel:[0, 1, 0]
	v_mov_b32_e32 v24, v27
	v_pk_fma_f32 v[90:91], v[202:203], v[26:27], v[90:91] op_sel_hi:[1, 0, 1]
	v_pk_fma_f32 v[88:89], v[200:201], v[26:27], v[88:89] op_sel_hi:[1, 0, 1]
	v_pk_fma_f32 v[134:135], v[202:203], v[24:25], v[102:103] op_sel_hi:[1, 0, 1]
	v_pk_fma_f32 v[136:137], v[200:201], v[24:25], v[100:101] op_sel_hi:[1, 0, 1]
	ds_read_b128 v[24:27], v116 offset:608
	s_waitcnt lgkmcnt(0)
	v_pk_fma_f32 v[82:83], v[202:203], v[24:25], v[82:83] op_sel_hi:[1, 0, 1]
	v_pk_fma_f32 v[80:81], v[200:201], v[24:25], v[80:81] op_sel_hi:[1, 0, 1]
	v_pk_fma_f32 v[78:79], v[202:203], v[24:25], v[78:79] op_sel:[0, 1, 0]
	v_pk_fma_f32 v[76:77], v[200:201], v[24:25], v[76:77] op_sel:[0, 1, 0]
	v_mov_b32_e32 v24, v27
	v_pk_fma_f32 v[74:75], v[202:203], v[26:27], v[74:75] op_sel_hi:[1, 0, 1]
	v_pk_fma_f32 v[72:73], v[200:201], v[26:27], v[72:73] op_sel_hi:[1, 0, 1]
	v_pk_fma_f32 v[138:139], v[202:203], v[24:25], v[86:87] op_sel_hi:[1, 0, 1]
	v_pk_fma_f32 v[140:141], v[200:201], v[24:25], v[84:85] op_sel_hi:[1, 0, 1]
	ds_read_b128 v[24:27], v116 offset:624
	s_waitcnt lgkmcnt(0)
; #define LAS __attribute__((address_space(3)))
; __device__ __forceinline__ void gemv24_item(const float* W, int N, int j0, LAS float* sc, LAS float* red, float (&res)[6], const int tid) {
;     ...
;     for (int kk = 0; kk < 64; ++kk) {
;         const f32x4 wv = *(const f32x4*)(w + (size_t)kk * N);
;         const LAS f32x4* s4 = (const LAS f32x4*)(sc + (ks * 64 + kk) * 24);
; #pragma unroll
;         for (int b4 = 0; b4 < 6; ++b4) { const f32x4 s = s4[b4]; acc[4 * b4] += wv * s[0]; acc[4 * b4 + 1] += wv * s[1]; acc[4 * b4 + 2] += wv * s[2]; acc[4 * b4 + 3] += wv * s[3]; }
;     }
;     ...
;     for (int bg = 0; bg < 3; ++bg) {
; #pragma unroll
;         for (int bb = 0; bb < 8; ++bb) {
;             f32x4 a = acc[8 * bg + bb];
;             a[0] += __shfl_xor(a[0], 32); a[1] += __shfl_xor(a[1], 32); a[2] += __shfl_xor(a[2], 32); a[3] += __shfl_xor(a[3], 32);
;             if (lane < 32) *(LAS f32x4*)(red + ((wave * 8 + bb) * 128 + cg * 4)) = a;
	v_pk_fma_f32 v[66:67], v[202:203], v[24:25], v[66:67] op_sel_hi:[1, 0, 1]
	v_pk_fma_f32 v[64:65], v[200:201], v[24:25], v[64:65] op_sel_hi:[1, 0, 1]
	v_pk_fma_f32 v[62:63], v[202:203], v[24:25], v[62:63] op_sel:[0, 1, 0]
	v_pk_fma_f32 v[60:61], v[200:201], v[24:25], v[60:61] op_sel:[0, 1, 0]
	v_mov_b32_e32 v24, v27
	v_pk_fma_f32 v[58:59], v[202:203], v[26:27], v[58:59] op_sel_hi:[1, 0, 1]
	v_pk_fma_f32 v[56:57], v[200:201], v[26:27], v[56:57] op_sel_hi:[1, 0, 1]
	v_pk_fma_f32 v[142:143], v[202:203], v[24:25], v[70:71] op_sel_hi:[1, 0, 1]
	v_pk_fma_f32 v[144:145], v[200:201], v[24:25], v[68:69] op_sel_hi:[1, 0, 1]
	ds_read_b128 v[24:27], v116 offset:640
	s_waitcnt lgkmcnt(0)
	v_pk_fma_f32 v[50:51], v[202:203], v[24:25], v[50:51] op_sel_hi:[1, 0, 1]
	v_pk_fma_f32 v[48:49], v[200:201], v[24:25], v[48:49] op_sel_hi:[1, 0, 1]
	v_pk_fma_f32 v[46:47], v[202:203], v[24:25], v[46:47] op_sel:[0, 1, 0]
	v_pk_fma_f32 v[44:45], v[200:201], v[24:25], v[44:45] op_sel:[0, 1, 0]
	v_mov_b32_e32 v24, v27
	v_pk_fma_f32 v[42:43], v[202:203], v[26:27], v[42:43] op_sel_hi:[1, 0, 1]
	v_pk_fma_f32 v[40:41], v[200:201], v[26:27], v[40:41] op_sel_hi:[1, 0, 1]
	v_pk_fma_f32 v[146:147], v[202:203], v[24:25], v[54:55] op_sel_hi:[1, 0, 1]
	v_pk_fma_f32 v[148:149], v[200:201], v[24:25], v[52:53] op_sel_hi:[1, 0, 1]
	ds_read_b128 v[24:27], v116 offset:656
	s_waitcnt lgkmcnt(0)
	v_pk_fma_f32 v[34:35], v[202:203], v[24:25], v[34:35] op_sel_hi:[1, 0, 1]
	v_pk_fma_f32 v[32:33], v[200:201], v[24:25], v[32:33] op_sel_hi:[1, 0, 1]
	v_pk_fma_f32 v[30:31], v[202:203], v[24:25], v[30:31] op_sel:[0, 1, 0]
	v_pk_fma_f32 v[28:29], v[200:201], v[24:25], v[28:29] op_sel:[0, 1, 0]
	v_mov_b32_e32 v24, v27
	v_pk_fma_f32 v[132:133], v[200:201], v[26:27], v[132:133] op_sel_hi:[1, 0, 1]
	v_pk_fma_f32 v[154:155], v[200:201], v[24:25], v[124:125] op_sel_hi:[1, 0, 1]
	v_lshl_add_u64 v[20:21], v[126:127], 0, s[34:35]
	v_pk_fma_f32 v[150:151], v[202:203], v[26:27], v[36:37] op_sel_hi:[1, 0, 1]
	v_pk_fma_f32 v[152:153], v[202:203], v[24:25], v[38:39] op_sel_hi:[1, 0, 1]
	ds_read_b128 v[24:27], v116 offset:672
	ds_read_b128 v[124:127], v116 offset:752
	s_waitcnt vmcnt(0) lgkmcnt(1)
	v_pk_fma_f32 v[114:115], v[206:207], v[24:25], v[114:115] op_sel_hi:[1, 0, 1]
	v_pk_fma_f32 v[112:113], v[204:205], v[24:25], v[112:113] op_sel_hi:[1, 0, 1]
	v_pk_fma_f32 v[110:111], v[206:207], v[24:25], v[110:111] op_sel:[0, 1, 0]
	v_pk_fma_f32 v[108:109], v[204:205], v[24:25], v[108:109] op_sel:[0, 1, 0]
	v_mov_b32_e32 v24, v27
	v_pk_fma_f32 v[106:107], v[206:207], v[26:27], v[106:107] op_sel_hi:[1, 0, 1]
	v_pk_fma_f32 v[104:105], v[204:205], v[26:27], v[104:105] op_sel_hi:[1, 0, 1]
	v_pk_fma_f32 v[102:103], v[206:207], v[24:25], v[130:131] op_sel_hi:[1, 0, 1]
	v_pk_fma_f32 v[100:101], v[204:205], v[24:25], v[128:129] op_sel_hi:[1, 0, 1]
	ds_read_b128 v[24:27], v116 offset:688
	s_waitcnt lgkmcnt(1)
	v_pk_fma_f32 v[34:35], v[206:207], v[124:125], v[34:35] op_sel_hi:[1, 0, 1]
	v_pk_fma_f32 v[32:33], v[204:205], v[124:125], v[32:33] op_sel_hi:[1, 0, 1]
	v_pk_fma_f32 v[30:31], v[206:207], v[124:125], v[30:31] op_sel:[0, 1, 0]
	v_pk_fma_f32 v[28:29], v[204:205], v[124:125], v[28:29] op_sel:[0, 1, 0]
	s_waitcnt lgkmcnt(0)
	v_pk_fma_f32 v[98:99], v[206:207], v[24:25], v[98:99] op_sel_hi:[1, 0, 1]
	v_pk_fma_f32 v[96:97], v[204:205], v[24:25], v[96:97] op_sel_hi:[1, 0, 1]
	v_pk_fma_f32 v[94:95], v[206:207], v[24:25], v[94:95] op_sel:[0, 1, 0]
	v_pk_fma_f32 v[92:93], v[204:205], v[24:25], v[92:93] op_sel:[0, 1, 0]
	v_mov_b32_e32 v24, v27
	v_pk_fma_f32 v[90:91], v[206:207], v[26:27], v[90:91] op_sel_hi:[1, 0, 1]
	v_pk_fma_f32 v[88:89], v[204:205], v[26:27], v[88:89] op_sel_hi:[1, 0, 1]
	v_pk_fma_f32 v[86:87], v[206:207], v[24:25], v[134:135] op_sel_hi:[1, 0, 1]
	v_pk_fma_f32 v[84:85], v[204:205], v[24:25], v[136:137] op_sel_hi:[1, 0, 1]
	ds_read_b128 v[24:27], v116 offset:704
	s_waitcnt lgkmcnt(0)
	v_pk_fma_f32 v[82:83], v[206:207], v[24:25], v[82:83] op_sel_hi:[1, 0, 1]
	v_pk_fma_f32 v[80:81], v[204:205], v[24:25], v[80:81] op_sel_hi:[1, 0, 1]
	v_pk_fma_f32 v[78:79], v[206:207], v[24:25], v[78:79] op_sel:[0, 1, 0]
	v_pk_fma_f32 v[76:77], v[204:205], v[24:25], v[76:77] op_sel:[0, 1, 0]
	v_mov_b32_e32 v24, v27
	v_pk_fma_f32 v[74:75], v[206:207], v[26:27], v[74:75] op_sel_hi:[1, 0, 1]
	v_pk_fma_f32 v[72:73], v[204:205], v[26:27], v[72:73] op_sel_hi:[1, 0, 1]
	v_pk_fma_f32 v[70:71], v[206:207], v[24:25], v[138:139] op_sel_hi:[1, 0, 1]
	v_pk_fma_f32 v[68:69], v[204:205], v[24:25], v[140:141] op_sel_hi:[1, 0, 1]
	ds_read_b128 v[24:27], v116 offset:720
	s_waitcnt lgkmcnt(0)
	v_pk_fma_f32 v[66:67], v[206:207], v[24:25], v[66:67] op_sel_hi:[1, 0, 1]
	v_pk_fma_f32 v[64:65], v[204:205], v[24:25], v[64:65] op_sel_hi:[1, 0, 1]
	v_pk_fma_f32 v[62:63], v[206:207], v[24:25], v[62:63] op_sel:[0, 1, 0]
	v_pk_fma_f32 v[60:61], v[204:205], v[24:25], v[60:61] op_sel:[0, 1, 0]
	v_mov_b32_e32 v24, v27
	v_pk_fma_f32 v[58:59], v[206:207], v[26:27], v[58:59] op_sel_hi:[1, 0, 1]
	v_pk_fma_f32 v[56:57], v[204:205], v[26:27], v[56:57] op_sel_hi:[1, 0, 1]
	v_pk_fma_f32 v[54:55], v[206:207], v[24:25], v[142:143] op_sel_hi:[1, 0, 1]
	v_pk_fma_f32 v[52:53], v[204:205], v[24:25], v[144:145] op_sel_hi:[1, 0, 1]
	ds_read_b128 v[24:27], v116 offset:736
	v_mov_b32_e32 v116, v127
	s_waitcnt lgkmcnt(0)
	v_pk_fma_f32 v[50:51], v[206:207], v[24:25], v[50:51] op_sel_hi:[1, 0, 1]
	v_pk_fma_f32 v[48:49], v[204:205], v[24:25], v[48:49] op_sel_hi:[1, 0, 1]
	v_pk_fma_f32 v[46:47], v[206:207], v[24:25], v[46:47] op_sel:[0, 1, 0]
	v_pk_fma_f32 v[44:45], v[204:205], v[24:25], v[44:45] op_sel:[0, 1, 0]
	v_mov_b32_e32 v24, v27
	v_pk_fma_f32 v[42:43], v[206:207], v[26:27], v[42:43] op_sel_hi:[1, 0, 1]
	v_pk_fma_f32 v[40:41], v[204:205], v[26:27], v[40:41] op_sel_hi:[1, 0, 1]
	v_pk_fma_f32 v[38:39], v[206:207], v[24:25], v[146:147] op_sel_hi:[1, 0, 1]
	v_pk_fma_f32 v[36:37], v[204:205], v[24:25], v[148:149] op_sel_hi:[1, 0, 1]
	v_pk_fma_f32 v[26:27], v[206:207], v[126:127], v[150:151] op_sel_hi:[1, 0, 1]
	v_pk_fma_f32 v[24:25], v[204:205], v[126:127], v[132:133] op_sel_hi:[1, 0, 1]
	v_pk_fma_f32 v[22:23], v[206:207], v[116:117], v[152:153] op_sel_hi:[1, 0, 1]
	v_pk_fma_f32 v[20:21], v[204:205], v[116:117], v[154:155] op_sel_hi:[1, 0, 1]
	s_cbranch_scc0 .LBB0_436
	v_xor_b32_e32 v18, 32, v226
	v_cmp_lt_i32_e32 vcc, v18, v228
	s_nop 1
	v_cndmask_b32_e32 v18, v226, v18, vcc
	v_lshlrev_b32_e32 v123, 2, v18
	ds_bpermute_b32 v18, v123, v112
	ds_bpermute_b32 v19, v123, v113
	ds_bpermute_b32 v116, v123, v114
	ds_bpermute_b32 v117, v123, v115
	s_and_saveexec_b64 s[34:35], s[44:45]
	s_cbranch_execz .LBB0_439
	s_waitcnt lgkmcnt(0)
	v_pk_add_f32 v[114:115], v[114:115], v[116:117]
	v_pk_add_f32 v[112:113], v[112:113], v[18:19]
	ds_write_b128 v118, v[112:115]

; __device__ __forceinline__ unsigned pk2(float lo, float hi) { f32x2_t v = {lo, hi}; bf16x2_t r = __builtin_convertvector(v, bf16x2_t); return __builtin_bit_cast(unsigned, r); }
; __device__ __forceinline__ void phase_norm_first(const Params& p, const int tid) {
;     const int wave = tid >> 6, lane = tid & 63;
;     const int gw = blockIdx.x * 8 + wave, NGW = gridDim.x * 8;
;     const f32x4* g4 = (const f32x4*)(p.norm_g) + lane;
;     const float* mod = (const float*)(p.ws + WS_MOD);
;     bf16* H = (bf16*)(p.ws + WS_H);
;     float* ssq = (float*)(p.ws + WS_SSQ);
;     for (int row = gw; row < T; row += NGW) {
;         const float* xr = row < TP ? p.xp + (size_t)row * D : p.xs + (size_t)(row - TP) * D;
;         const int b = batch_of_row(row);
;         const f32x4* sc4 = (const f32x4*)(mod + ((size_t)b * 9 + 1) * D) + lane;
;         const f32x4* x4 = (const f32x4*)xr + lane;
;         f32x4 v[4]; float s = 0.f;
; #pragma unroll
;         for (int j = 0; j < 4; ++j) { v[j] = x4[64 * j]; s += (v[j].x * v[j].x + v[j].y * v[j].y) + (v[j].z * v[j].z + v[j].w * v[j].w); }
;         s = wave_sum(s);
;         if (lane == 0) ssq[row] = s;
;         u32x2* o8 = (u32x2*)(H + (size_t)row * D) + lane;
; #pragma unroll
;         for (int j = 0; j < 4; ++j) {
;             const f32x4 y = v[j] * g4[64 * j] * (sc4[64 * j] + 1.0f);
;             u32x2 w; w.x = pk2(y.x, y.y); w.y = pk2(y.z, y.w);
;             o8[64 * j] = w;
;         }
;     }
.LBB0_500:
	s_or_b64 exec, exec, s[30:31]
	v_readlane_b32 s0, v253, 22
	v_ashrrev_i32_e32 v0, 6, v13
	s_nop 0
	v_add_u32_e32 v16, s0, v0
	s_mov_b32 s0, 0x10000
	v_cmp_gt_i32_e32 vcc, s0, v16
	s_and_saveexec_b64 s[30:31], vcc
	v_readlane_b32 s46, v255, 2
	v_readlane_b32 s47, v255, 3
	s_cbranch_execz .LBB0_509
	v_cmp_lt_i32_e32 vcc, v227, v228
	v_and_b32_e32 v0, 63, v13
	v_readlane_b32 s0, v254, 13
	v_cndmask_b32_e32 v1, v226, v227, vcc
	v_cmp_lt_i32_e32 vcc, v229, v228
	v_lshlrev_b32_e32 v30, 2, v1
	v_lshlrev_b32_e32 v2, 3, v0
	v_cndmask_b32_e32 v1, v226, v229, vcc
	v_cmp_lt_i32_e32 vcc, v230, v228
	v_lshlrev_b32_e32 v31, 2, v1
	v_mov_b32_e32 v3, v161
	v_cndmask_b32_e32 v1, v226, v230, vcc
	v_lshlrev_b32_e32 v32, 2, v1
	v_xor_b32_e32 v1, 8, v226
	v_cmp_lt_i32_e32 vcc, v1, v228
	v_readlane_b32 s1, v254, 14
	v_ashrrev_i32_e32 v17, 31, v16
	v_cndmask_b32_e32 v1, v226, v1, vcc
	v_lshlrev_b32_e32 v33, 2, v1
	v_xor_b32_e32 v1, 16, v226
	v_cmp_lt_i32_e32 vcc, v1, v228
	v_lshl_add_u64 v[20:21], s[0:1], 0, v[2:3]
	v_readlane_b32 s0, v253, 59
	v_cndmask_b32_e32 v1, v226, v1, vcc
	v_lshlrev_b32_e32 v34, 2, v1
	v_xor_b32_e32 v1, 32, v226
	v_cmp_lt_i32_e32 vcc, v1, v228
	v_lshlrev_b32_e32 v160, 4, v0
	v_readlane_b32 s1, v253, 60
	v_cndmask_b32_e32 v1, v226, v1, vcc
	s_ashr_i32 s29, s28, 31
	v_lshlrev_b64 v[2:3], 12, v[16:17]
	v_lshl_add_u64 v[18:19], s[80:81], 0, v[160:161]
	v_lshl_add_u64 v[22:23], s[0:1], 0, v[160:161]
	v_lshlrev_b32_e32 v35, 2, v1
	v_cmp_eq_u32_e32 vcc, 0, v0
	v_lshl_add_u64 v[24:25], s[68:69], 0, v[2:3]
	s_lshl_b64 s[34:35], s[28:29], 12
	s_mov_b64 s[36:37], 0
	v_lshlrev_b32_e32 v160, 4, v0
	global_load_dwordx4 v[60:63], v[18:19], off
	global_load_dwordx4 v[64:67], v[18:19], off offset:1024
	global_load_dwordx4 v[68:71], v[18:19], off offset:2048
	global_load_dwordx4 v[72:75], v[18:19], off offset:3072
.LBB0_503:
	s_mov_b32 s0, 0x8000
	v_cmp_gt_i32_e64 s[42:43], s0, v16
	s_movk_i32 s0, 0x7fff
	v_cmp_lt_i32_e64 s[44:45], s0, v16
	v_add_u32_e32 v26, 0xffff8000, v16
	s_and_saveexec_b64 s[0:1], s[44:45]
	s_xor_b64 s[40:41], exec, s[0:1]
	v_add_u32_e32 v26, 0xffff8000, v16
	v_mov_b32_e32 v27, v161
	v_lshlrev_b64 v[0:1], 12, v[26:27]
	v_lshl_add_u64 v[0:1], s[70:71], 0, v[0:1]
	v_mov_b32_e32 v28, v16
	v_mov_b32_e32 v29, v161
	s_andn2_saveexec_b64 s[40:41], s[40:41]
	v_mov_b64_e32 v[28:29], v[16:17]
	v_mov_b64_e32 v[0:1], v[24:25]
	s_or_b64 exec, exec, s[40:41]
	v_lshl_add_u64 v[0:1], v[0:1], 0, v[160:161]
	global_load_dwordx4 v[12:15], v[0:1], off
	global_load_dwordx4 v[8:11], v[0:1], off offset:1024
	global_load_dwordx4 v[4:7], v[0:1], off offset:2048
	global_load_dwordx4 v[40:43], v[0:1], off offset:3072
	v_lshrrev_b32_e32 v26, 12, v26
	v_ashrrev_i32_e32 v27, 11, v16
	v_add_u32_e32 v26, 16, v26
	v_cndmask_b32_e64 v26, v26, v27, s[42:43]
	v_mul_hi_i32_i24_e32 v27, 0x9000, v26
	v_mul_i32_i24_e32 v26, 0x9000, v26
	v_lshl_add_u64 v[36:37], v[22:23], 0, v[26:27]
	global_load_dwordx4 v[44:47], v[36:37], off
	global_load_dwordx4 v[48:51], v[36:37], off offset:1024
	global_load_dwordx4 v[52:55], v[36:37], off offset:2048
	global_load_dwordx4 v[56:59], v[36:37], off offset:3072
	v_lshlrev_b64 v[26:27], 11, v[28:29]
	v_lshl_add_u64 v[38:39], v[20:21], 0, v[26:27]
	v_lshl_add_u64 v[76:77], v[28:29], 2, s[48:49]
	s_waitcnt vmcnt(4)
	v_mul_f32_e32 v2, v13, v13
	v_mul_f32_e32 v3, v15, v15
	v_fmac_f32_e32 v2, v12, v12
	v_fmac_f32_e32 v3, v14, v14
	v_add_f32_e32 v2, v2, v3
	v_mul_f32_e32 v3, v9, v9
	v_mul_f32_e32 v27, v11, v11
	v_fmac_f32_e32 v3, v8, v8
	v_fmac_f32_e32 v27, v10, v10
	v_add_f32_e32 v3, v3, v27
	v_add_f32_e32 v2, v2, v3
	v_mul_f32_e32 v3, v5, v5
	v_mul_f32_e32 v27, v7, v7
	v_fmac_f32_e32 v3, v4, v4
	v_fmac_f32_e32 v27, v6, v6
	v_add_f32_e32 v3, v3, v27
	v_add_f32_e32 v27, v2, v3
	v_mul_f32_e32 v2, v41, v41
	v_mul_f32_e32 v3, v43, v43
	v_fmac_f32_e32 v2, v40, v40
	v_fmac_f32_e32 v3, v42, v42
	v_add_f32_e32 v2, v2, v3
	v_add_f32_e32 v27, v27, v2
	ds_bpermute_b32 v36, v30, v27
	s_waitcnt lgkmcnt(0)
	v_add_f32_e32 v27, v27, v36
	ds_bpermute_b32 v36, v31, v27
	s_waitcnt lgkmcnt(0)
	v_add_f32_e32 v27, v27, v36
	ds_bpermute_b32 v36, v32, v27
	s_waitcnt lgkmcnt(0)
	v_add_f32_e32 v27, v27, v36
	ds_bpermute_b32 v36, v33, v27
	s_waitcnt lgkmcnt(0)
	v_add_f32_e32 v27, v27, v36
	ds_bpermute_b32 v36, v34, v27
	s_waitcnt lgkmcnt(0)
	v_add_f32_e32 v27, v27, v36
	ds_bpermute_b32 v36, v35, v27
	s_waitcnt lgkmcnt(0)
	v_add_f32_e32 v27, v27, v36
	s_waitcnt vmcnt(0)
	s_and_saveexec_b64 s[40:41], vcc
	global_store_dword v[76:77], v27, off
	s_or_b64 exec, exec, s[40:41]
	v_pk_mul_f32 v[12:13], v[60:61], v[12:13]
	v_pk_mul_f32 v[14:15], v[62:63], v[14:15]
	v_pk_add_f32 v[44:45], v[44:45], 1.0 op_sel_hi:[1,0]
	v_pk_add_f32 v[46:47], v[46:47], 1.0 op_sel_hi:[1,0]
	v_pk_mul_f32 v[12:13], v[12:13], v[44:45]
	v_pk_mul_f32 v[14:15], v[14:15], v[46:47]
	v_cvt_pk_bf16_f32 v12, v12, v13
	v_cvt_pk_bf16_f32 v13, v14, v15
	global_store_dwordx2 v[38:39], v[12:13], off
	v_pk_mul_f32 v[8:9], v[64:65], v[8:9]
	v_pk_mul_f32 v[10:11], v[66:67], v[10:11]
	v_pk_add_f32 v[48:49], v[48:49], 1.0 op_sel_hi:[1,0]
	v_pk_add_f32 v[50:51], v[50:51], 1.0 op_sel_hi:[1,0]
	v_pk_mul_f32 v[8:9], v[8:9], v[48:49]
	v_pk_mul_f32 v[10:11], v[10:11], v[50:51]
	v_cvt_pk_bf16_f32 v8, v8, v9
	v_cvt_pk_bf16_f32 v9, v10, v11
	global_store_dwordx2 v[38:39], v[8:9], off offset:512
	v_pk_mul_f32 v[4:5], v[68:69], v[4:5]
	v_pk_mul_f32 v[6:7], v[70:71], v[6:7]
	v_pk_add_f32 v[52:53], v[52:53], 1.0 op_sel_hi:[1,0]
	v_pk_add_f32 v[54:55], v[54:55], 1.0 op_sel_hi:[1,0]
	v_pk_mul_f32 v[4:5], v[4:5], v[52:53]
	v_pk_mul_f32 v[6:7], v[6:7], v[54:55]
	v_cvt_pk_bf16_f32 v4, v4, v5
	v_cvt_pk_bf16_f32 v5, v6, v7
	global_store_dwordx2 v[38:39], v[4:5], off offset:1024
	v_pk_mul_f32 v[40:41], v[72:73], v[40:41]
	v_pk_mul_f32 v[42:43], v[74:75], v[42:43]
	v_pk_add_f32 v[56:57], v[56:57], 1.0 op_sel_hi:[1,0]
	v_pk_add_f32 v[58:59], v[58:59], 1.0 op_sel_hi:[1,0]
	v_pk_mul_f32 v[40:41], v[40:41], v[56:57]
	v_pk_mul_f32 v[42:43], v[42:43], v[58:59]
	v_cvt_pk_bf16_f32 v40, v40, v41
	v_cvt_pk_bf16_f32 v41, v42, v43
	global_store_dwordx2 v[38:39], v[40:41], off offset:1536
	v_lshl_add_u64 v[16:17], v[16:17], 0, s[28:29]
	v_cmp_lt_i32_e64 s[42:43], s60, v16
	v_lshl_add_u64 v[24:25], v[24:25], 0, s[34:35]
	s_or_b64 s[36:37], s[42:43], s[36:37]
	s_andn2_b64 exec, exec, s[36:37]
	s_cbranch_execnz .LBB0_503

; #define LAS __attribute__((address_space(3)))
; __device__ __forceinline__ void gemv24_item(const float* W, int N, int j0, LAS float* sc, LAS float* red, float (&res)[6], const int tid) {
;     ...
;     for (int kk = 0; kk < 64; ++kk) {
;         const f32x4 wv = *(const f32x4*)(w + (size_t)kk * N);
;         const LAS f32x4* s4 = (const LAS f32x4*)(sc + (ks * 64 + kk) * 24);
; #pragma unroll
;         for (int b4 = 0; b4 < 6; ++b4) { const f32x4 s = s4[b4]; acc[4 * b4] += wv * s[0]; acc[4 * b4 + 1] += wv * s[1]; acc[4 * b4 + 2] += wv * s[2]; acc[4 * b4 + 3] += wv * s[3]; }
;     }
.LBB0_523:
	v_lshl_add_u64 v[208:209], v[20:21], 0, s[30:31]
	global_load_dwordx4 v[176:179], v[208:209], off
	v_add_co_u32_e64 v208, s[42:43], s67, v208
	s_nop 1
	v_addc_co_u32_e64 v209, s[42:43], 0, v209, s[42:43]
	global_load_dwordx4 v[180:183], v[208:209], off
	v_add_co_u32_e64 v208, s[42:43], s67, v208
	s_nop 1
	v_addc_co_u32_e64 v209, s[42:43], 0, v209, s[42:43]
	global_load_dwordx4 v[184:187], v[208:209], off
	v_add_co_u32_e64 v208, s[42:43], s67, v208
	s_nop 1
	v_addc_co_u32_e64 v209, s[42:43], 0, v209, s[42:43]
	global_load_dwordx4 v[188:191], v[208:209], off
	v_add_co_u32_e64 v208, s[42:43], s67, v208
	s_nop 1
	v_addc_co_u32_e64 v209, s[42:43], 0, v209, s[42:43]
	global_load_dwordx4 v[192:195], v[208:209], off
	v_add_co_u32_e64 v208, s[42:43], s67, v208
	s_nop 1
	v_addc_co_u32_e64 v209, s[42:43], 0, v209, s[42:43]
	global_load_dwordx4 v[196:199], v[208:209], off
	v_add_co_u32_e64 v208, s[42:43], s67, v208
	s_nop 1
	v_addc_co_u32_e64 v209, s[42:43], 0, v209, s[42:43]
	global_load_dwordx4 v[200:203], v[208:209], off
	v_add_co_u32_e64 v208, s[42:43], s67, v208
	s_nop 1
	v_addc_co_u32_e64 v209, s[42:43], 0, v209, s[42:43]
	global_load_dwordx4 v[204:207], v[208:209], off
	v_lshl_add_u64 v[22:23], v[20:21], 0, s[30:31]
	ds_read_b128 v[122:125], v174
	ds_read_b128 v[132:135], v174 offset:16
	ds_read_b128 v[136:139], v174 offset:32
	ds_read_b128 v[140:143], v174 offset:48
	s_mov_b32 s0, 0x24000
	s_add_u32 s30, s30, 0x48000
	s_addc_u32 s31, s31, 0
	s_cmp_eq_u32 s30, 0x240000
	s_waitcnt vmcnt(7) lgkmcnt(3)
	v_pk_fma_f32 v[120:121], v[176:177], v[124:125], v[96:97] op_sel_hi:[1, 0, 1]
	v_mov_b32_e32 v96, v125
	v_pk_fma_f32 v[118:119], v[178:179], v[122:123], v[118:119] op_sel_hi:[1, 0, 1]
	v_pk_fma_f32 v[128:129], v[176:177], v[122:123], v[116:117] op_sel_hi:[1, 0, 1]
	v_pk_fma_f32 v[116:117], v[178:179], v[122:123], v[110:111] op_sel:[0, 1, 0]
	v_pk_fma_f32 v[130:131], v[176:177], v[122:123], v[108:109] op_sel:[0, 1, 0]
	v_pk_fma_f32 v[122:123], v[178:179], v[124:125], v[100:101] op_sel_hi:[1, 0, 1]
	v_pk_fma_f32 v[124:125], v[176:177], v[96:97], v[80:81] op_sel_hi:[1, 0, 1]
	v_pk_fma_f32 v[126:127], v[178:179], v[96:97], v[84:85] op_sel_hi:[1, 0, 1]
	s_waitcnt lgkmcnt(2)
	v_pk_fma_f32 v[96:97], v[178:179], v[132:133], v[114:115] op_sel_hi:[1, 0, 1]
	v_pk_fma_f32 v[110:111], v[176:177], v[132:133], v[112:113] op_sel_hi:[1, 0, 1]
	v_pk_fma_f32 v[100:101], v[178:179], v[132:133], v[106:107] op_sel:[0, 1, 0]
	v_pk_fma_f32 v[112:113], v[176:177], v[132:133], v[102:103] op_sel:[0, 1, 0]
	v_pk_fma_f32 v[102:103], v[176:177], v[134:135], v[90:91] op_sel_hi:[1, 0, 1]
	v_pk_fma_f32 v[94:95], v[178:179], v[134:135], v[94:95] op_sel_hi:[1, 0, 1]
	v_mov_b32_e32 v80, v135
	ds_read_b128 v[132:135], v174 offset:64
	v_pk_fma_f32 v[106:107], v[176:177], v[80:81], v[74:75] op_sel_hi:[1, 0, 1]
	v_pk_fma_f32 v[108:109], v[178:179], v[80:81], v[78:79] op_sel_hi:[1, 0, 1]
	s_waitcnt lgkmcnt(2)
	v_pk_fma_f32 v[80:81], v[176:177], v[138:139], v[68:69] op_sel_hi:[1, 0, 1]
	v_mov_b32_e32 v68, v139
	v_pk_fma_f32 v[84:85], v[178:179], v[68:69], v[62:63] op_sel_hi:[1, 0, 1]
	s_waitcnt lgkmcnt(1)
	v_pk_fma_f32 v[62:63], v[178:179], v[140:141], v[76:77] op_sel:[0, 1, 0]
	v_mov_b32_e32 v76, v143
	v_pk_fma_f32 v[56:57], v[176:177], v[76:77], v[56:57] op_sel_hi:[1, 0, 1]
	v_pk_fma_f32 v[58:59], v[178:179], v[76:77], v[58:59] op_sel_hi:[1, 0, 1]
	s_waitcnt lgkmcnt(0)
	v_pk_fma_f32 v[54:55], v[178:179], v[132:133], v[54:55] op_sel_hi:[1, 0, 1]
	v_pk_fma_f32 v[52:53], v[176:177], v[132:133], v[52:53] op_sel_hi:[1, 0, 1]
	v_pk_fma_f32 v[50:51], v[178:179], v[132:133], v[50:51] op_sel:[0, 1, 0]
	v_pk_fma_f32 v[48:49], v[176:177], v[132:133], v[48:49] op_sel:[0, 1, 0]
	v_pk_fma_f32 v[44:45], v[176:177], v[134:135], v[44:45] op_sel_hi:[1, 0, 1]
	v_pk_fma_f32 v[46:47], v[178:179], v[134:135], v[46:47] op_sel_hi:[1, 0, 1]
	v_mov_b32_e32 v76, v135
	ds_read_b128 v[132:135], v174 offset:80
	v_pk_fma_f32 v[90:91], v[176:177], v[136:137], v[98:99] op_sel_hi:[1, 0, 1]
	v_pk_fma_f32 v[78:79], v[178:179], v[136:137], v[88:89] op_sel:[0, 1, 0]
	v_pk_fma_f32 v[88:89], v[176:177], v[136:137], v[82:83] op_sel:[0, 1, 0]
	v_pk_fma_f32 v[82:83], v[176:177], v[68:69], v[60:61] op_sel_hi:[1, 0, 1]
	s_waitcnt lgkmcnt(0)
	v_pk_fma_f32 v[98:99], v[176:177], v[132:133], v[40:41] op_sel_hi:[1, 0, 1]
	v_mov_b32_e32 v40, v135
	v_pk_fma_f32 v[68:69], v[176:177], v[140:141], v[86:87] op_sel_hi:[1, 0, 1]
	v_pk_fma_f32 v[70:71], v[176:177], v[140:141], v[70:71] op_sel:[0, 1, 0]
	v_pk_fma_f32 v[64:65], v[176:177], v[142:143], v[64:65] op_sel_hi:[1, 0, 1]
	v_pk_fma_f32 v[36:37], v[176:177], v[76:77], v[36:37] op_sel_hi:[1, 0, 1]
	v_pk_fma_f32 v[32:33], v[176:177], v[132:133], v[32:33] op_sel:[0, 1, 0]
	v_pk_fma_f32 v[28:29], v[176:177], v[134:135], v[28:29] op_sel_hi:[1, 0, 1]
	v_pk_fma_f32 v[24:25], v[176:177], v[40:41], v[24:25] op_sel_hi:[1, 0, 1]
	v_add_co_u32_e64 v0, s[42:43], s67, v22
	v_pk_fma_f32 v[74:75], v[178:179], v[136:137], v[104:105] op_sel_hi:[1, 0, 1]
	s_nop 0
	v_addc_co_u32_e64 v1, s[42:43], 0, v23, s[42:43]
	v_pk_fma_f32 v[72:73], v[178:179], v[138:139], v[72:73] op_sel_hi:[1, 0, 1]
	v_pk_fma_f32 v[60:61], v[178:179], v[140:141], v[92:93] op_sel_hi:[1, 0, 1]
	v_pk_fma_f32 v[66:67], v[178:179], v[142:143], v[66:67] op_sel_hi:[1, 0, 1]
	v_pk_fma_f32 v[38:39], v[178:179], v[76:77], v[38:39] op_sel_hi:[1, 0, 1]
	v_pk_fma_f32 v[92:93], v[178:179], v[132:133], v[42:43] op_sel_hi:[1, 0, 1]
	v_pk_fma_f32 v[34:35], v[178:179], v[132:133], v[34:35] op_sel:[0, 1, 0]
	v_pk_fma_f32 v[30:31], v[178:179], v[134:135], v[30:31] op_sel_hi:[1, 0, 1]
	v_pk_fma_f32 v[26:27], v[178:179], v[40:41], v[26:27] op_sel_hi:[1, 0, 1]
	ds_read_b128 v[40:43], v174 offset:96
	s_waitcnt vmcnt(6) lgkmcnt(0)
; #define LAS __attribute__((address_space(3)))
; __device__ __forceinline__ void gemv24_item(const float* W, int N, int j0, LAS float* sc, LAS float* red, float (&res)[6], const int tid) {
;     ...
;     for (int kk = 0; kk < 64; ++kk) {
;         const f32x4 wv = *(const f32x4*)(w + (size_t)kk * N);
;         const LAS f32x4* s4 = (const LAS f32x4*)(sc + (ks * 64 + kk) * 24);
; #pragma unroll
;         for (int b4 = 0; b4 < 6; ++b4) { const f32x4 s = s4[b4]; acc[4 * b4] += wv * s[0]; acc[4 * b4 + 1] += wv * s[1]; acc[4 * b4 + 2] += wv * s[2]; acc[4 * b4 + 3] += wv * s[3]; }
;     }
	v_pk_fma_f32 v[148:149], v[182:183], v[40:41], v[116:117] op_sel:[0, 1, 0]
	ds_read_b128 v[114:117], v174 offset:112
	v_pk_fma_f32 v[138:139], v[180:181], v[40:41], v[128:129] op_sel_hi:[1, 0, 1]
	v_pk_fma_f32 v[146:147], v[182:183], v[40:41], v[118:119] op_sel_hi:[1, 0, 1]
	v_pk_fma_f32 v[140:141], v[180:181], v[40:41], v[130:131] op_sel:[0, 1, 0]
	v_mov_b32_e32 v40, v43
	v_pk_fma_f32 v[144:145], v[180:181], v[40:41], v[124:125] op_sel_hi:[1, 0, 1]
	v_pk_fma_f32 v[152:153], v[182:183], v[40:41], v[126:127] op_sel_hi:[1, 0, 1]
	s_waitcnt lgkmcnt(0)
	v_pk_fma_f32 v[40:41], v[182:183], v[114:115], v[96:97] op_sel_hi:[1, 0, 1]
	v_pk_fma_f32 v[134:135], v[182:183], v[116:117], v[94:95] op_sel_hi:[1, 0, 1]
	ds_read_b128 v[94:97], v174 offset:128
	v_mov_b32_e32 v76, v117
	v_pk_fma_f32 v[126:127], v[180:181], v[76:77], v[106:107] op_sel_hi:[1, 0, 1]
	v_pk_fma_f32 v[124:125], v[180:181], v[116:117], v[102:103] op_sel_hi:[1, 0, 1]
	v_pk_fma_f32 v[142:143], v[180:181], v[42:43], v[120:121] op_sel_hi:[1, 0, 1]
	s_waitcnt lgkmcnt(0)
	v_pk_fma_f32 v[128:129], v[182:183], v[96:97], v[72:73] op_sel_hi:[1, 0, 1]
	v_mov_b32_e32 v72, v97
	v_pk_fma_f32 v[106:107], v[182:183], v[94:95], v[74:75] op_sel_hi:[1, 0, 1]
	v_pk_fma_f32 v[118:119], v[180:181], v[72:73], v[82:83] op_sel_hi:[1, 0, 1]
	v_pk_fma_f32 v[132:133], v[182:183], v[72:73], v[84:85] op_sel_hi:[1, 0, 1]
	ds_read_b128 v[72:75], v174 offset:144
	v_pk_fma_f32 v[116:117], v[180:181], v[96:97], v[80:81] op_sel_hi:[1, 0, 1]
	v_pk_fma_f32 v[150:151], v[182:183], v[42:43], v[122:123] op_sel_hi:[1, 0, 1]
	v_pk_fma_f32 v[42:43], v[180:181], v[114:115], v[110:111] op_sel_hi:[1, 0, 1]
	v_pk_fma_f32 v[136:137], v[182:183], v[76:77], v[108:109] op_sel_hi:[1, 0, 1]
	s_waitcnt lgkmcnt(0)
	v_pk_fma_f32 v[96:97], v[180:181], v[74:75], v[64:65] op_sel_hi:[1, 0, 1]
	v_pk_fma_f32 v[64:65], v[182:183], v[74:75], v[66:67] op_sel_hi:[1, 0, 1]
	v_mov_b32_e32 v66, v75
	v_pk_fma_f32 v[108:109], v[180:181], v[66:67], v[56:57] op_sel_hi:[1, 0, 1]
	v_pk_fma_f32 v[110:111], v[182:183], v[66:67], v[58:59] op_sel_hi:[1, 0, 1]
	ds_read_b128 v[56:59], v174 offset:160
	v_pk_fma_f32 v[130:131], v[182:183], v[114:115], v[100:101] op_sel:[0, 1, 0]
	v_pk_fma_f32 v[122:123], v[180:181], v[114:115], v[112:113] op_sel:[0, 1, 0]
	v_pk_fma_f32 v[112:113], v[180:181], v[94:95], v[90:91] op_sel_hi:[1, 0, 1]
	v_pk_fma_f32 v[114:115], v[180:181], v[94:95], v[88:89] op_sel:[0, 1, 0]
	s_waitcnt lgkmcnt(0)
	v_pk_fma_f32 v[82:83], v[180:181], v[58:59], v[44:45] op_sel_hi:[1, 0, 1]
	v_mov_b32_e32 v44, v59
	v_pk_fma_f32 v[86:87], v[180:181], v[44:45], v[36:37] op_sel_hi:[1, 0, 1]
	v_pk_fma_f32 v[84:85], v[182:183], v[44:45], v[38:39] op_sel_hi:[1, 0, 1]
	ds_read_b128 v[36:39], v174 offset:176
	v_pk_fma_f32 v[74:75], v[180:181], v[56:57], v[52:53] op_sel_hi:[1, 0, 1]
	v_pk_fma_f32 v[76:77], v[182:183], v[56:57], v[50:51] op_sel:[0, 1, 0]
	ds_read_b128 v[50:53], v174 offset:208
	v_pk_fma_f32 v[120:121], v[182:183], v[94:95], v[78:79] op_sel:[0, 1, 0]
	s_waitcnt lgkmcnt(1)
	v_pk_fma_f32 v[100:101], v[180:181], v[38:39], v[28:29] op_sel_hi:[1, 0, 1]
	v_mov_b32_e32 v28, v39
	v_pk_fma_f32 v[68:69], v[180:181], v[72:73], v[68:69] op_sel_hi:[1, 0, 1]
	v_pk_fma_f32 v[70:71], v[180:181], v[72:73], v[70:71] op_sel:[0, 1, 0]
	v_pk_fma_f32 v[78:79], v[180:181], v[56:57], v[48:49] op_sel:[0, 1, 0]
	v_pk_fma_f32 v[90:91], v[180:181], v[36:37], v[98:99] op_sel_hi:[1, 0, 1]
	v_pk_fma_f32 v[94:95], v[180:181], v[36:37], v[32:33] op_sel:[0, 1, 0]
	v_pk_fma_f32 v[104:105], v[180:181], v[28:29], v[24:25] op_sel_hi:[1, 0, 1]
	v_add_co_u32_e64 v0, s[42:43], s8, v22
	v_pk_fma_f32 v[60:61], v[182:183], v[72:73], v[60:61] op_sel_hi:[1, 0, 1]
	s_nop 0
	v_addc_co_u32_e64 v1, s[42:43], 0, v23, s[42:43]
	v_pk_fma_f32 v[62:63], v[182:183], v[72:73], v[62:63] op_sel:[0, 1, 0]
	v_pk_fma_f32 v[72:73], v[182:183], v[56:57], v[54:55] op_sel_hi:[1, 0, 1]
	v_pk_fma_f32 v[80:81], v[182:183], v[58:59], v[46:47] op_sel_hi:[1, 0, 1]
	v_pk_fma_f32 v[88:89], v[182:183], v[36:37], v[92:93] op_sel_hi:[1, 0, 1]
	v_pk_fma_f32 v[92:93], v[182:183], v[36:37], v[34:35] op_sel:[0, 1, 0]
	v_pk_fma_f32 v[98:99], v[182:183], v[38:39], v[30:31] op_sel_hi:[1, 0, 1]
	v_pk_fma_f32 v[102:103], v[182:183], v[28:29], v[26:27] op_sel_hi:[1, 0, 1]
	ds_read_b128 v[34:37], v174 offset:192
	ds_read_b128 v[56:59], v174 offset:224
	s_waitcnt lgkmcnt(2)
	v_mov_b32_e32 v54, v53
	s_waitcnt lgkmcnt(1)
	v_mov_b32_e32 v38, v37
	s_waitcnt vmcnt(5)
	v_pk_fma_f32 v[40:41], v[186:187], v[50:51], v[40:41] op_sel_hi:[1, 0, 1]
	v_pk_fma_f32 v[42:43], v[184:185], v[50:51], v[42:43] op_sel_hi:[1, 0, 1]
	v_pk_fma_f32 v[44:45], v[186:187], v[50:51], v[130:131] op_sel:[0, 1, 0]
	v_pk_fma_f32 v[46:47], v[184:185], v[50:51], v[122:123] op_sel:[0, 1, 0]
	v_pk_fma_f32 v[48:49], v[186:187], v[52:53], v[134:135] op_sel_hi:[1, 0, 1]
	v_pk_fma_f32 v[50:51], v[184:185], v[52:53], v[124:125] op_sel_hi:[1, 0, 1]
	v_pk_fma_f32 v[52:53], v[186:187], v[54:55], v[136:137] op_sel_hi:[1, 0, 1]
	v_pk_fma_f32 v[54:55], v[184:185], v[54:55], v[126:127] op_sel_hi:[1, 0, 1]
	s_waitcnt lgkmcnt(0)
	v_pk_fma_f32 v[122:123], v[184:185], v[56:57], v[112:113] op_sel_hi:[1, 0, 1]
	v_pk_fma_f32 v[126:127], v[184:185], v[56:57], v[114:115] op_sel:[0, 1, 0]
	ds_read_b128 v[112:115], v174 offset:240
	v_pk_fma_f32 v[106:107], v[186:187], v[56:57], v[106:107] op_sel_hi:[1, 0, 1]
	v_pk_fma_f32 v[124:125], v[186:187], v[56:57], v[120:121] op_sel:[0, 1, 0]
	v_mov_b32_e32 v56, v59
	v_pk_fma_f32 v[130:131], v[184:185], v[58:59], v[116:117] op_sel_hi:[1, 0, 1]
	v_pk_fma_f32 v[132:133], v[186:187], v[56:57], v[132:133] op_sel_hi:[1, 0, 1]
	v_pk_fma_f32 v[134:135], v[184:185], v[56:57], v[118:119] op_sel_hi:[1, 0, 1]
	ds_read_b128 v[116:119], v174 offset:288
	s_waitcnt lgkmcnt(1)
; #define LAS __attribute__((address_space(3)))
; __device__ __forceinline__ void gemv24_item(const float* W, int N, int j0, LAS float* sc, LAS float* red, float (&res)[6], const int tid) {
;     ...
;     for (int kk = 0; kk < 64; ++kk) {
;         const f32x4 wv = *(const f32x4*)(w + (size_t)kk * N);
;         const LAS f32x4* s4 = (const LAS f32x4*)(sc + (ks * 64 + kk) * 24);
; #pragma unroll
;         for (int b4 = 0; b4 < 6; ++b4) { const f32x4 s = s4[b4]; acc[4 * b4] += wv * s[0]; acc[4 * b4 + 1] += wv * s[1]; acc[4 * b4 + 2] += wv * s[2]; acc[4 * b4 + 3] += wv * s[3]; }
;     }
	v_pk_fma_f32 v[56:57], v[186:187], v[112:113], v[60:61] op_sel_hi:[1, 0, 1]
	v_pk_fma_f32 v[60:61], v[186:187], v[112:113], v[62:63] op_sel:[0, 1, 0]
	v_pk_fma_f32 v[62:63], v[184:185], v[112:113], v[70:71] op_sel:[0, 1, 0]
	v_mov_b32_e32 v70, v115
	v_pk_fma_f32 v[128:129], v[186:187], v[58:59], v[128:129] op_sel_hi:[1, 0, 1]
	v_pk_fma_f32 v[58:59], v[184:185], v[112:113], v[68:69] op_sel_hi:[1, 0, 1]
	v_pk_fma_f32 v[68:69], v[186:187], v[70:71], v[110:111] op_sel_hi:[1, 0, 1]
	v_pk_fma_f32 v[70:71], v[184:185], v[70:71], v[108:109] op_sel_hi:[1, 0, 1]
	ds_read_b128 v[108:111], v174 offset:256
	v_pk_fma_f32 v[66:67], v[184:185], v[114:115], v[96:97] op_sel_hi:[1, 0, 1]
	v_pk_fma_f32 v[24:25], v[186:187], v[34:35], v[146:147] op_sel_hi:[1, 0, 1]
	v_pk_fma_f32 v[26:27], v[184:185], v[34:35], v[138:139] op_sel_hi:[1, 0, 1]
	v_pk_fma_f32 v[28:29], v[186:187], v[34:35], v[148:149] op_sel:[0, 1, 0]
	s_waitcnt lgkmcnt(0)
	v_pk_fma_f32 v[72:73], v[186:187], v[108:109], v[72:73] op_sel_hi:[1, 0, 1]
	v_pk_fma_f32 v[74:75], v[184:185], v[108:109], v[74:75] op_sel_hi:[1, 0, 1]
	v_pk_fma_f32 v[76:77], v[186:187], v[108:109], v[76:77] op_sel:[0, 1, 0]
	v_pk_fma_f32 v[78:79], v[184:185], v[108:109], v[78:79] op_sel:[0, 1, 0]
	v_pk_fma_f32 v[80:81], v[186:187], v[110:111], v[80:81] op_sel_hi:[1, 0, 1]
	v_pk_fma_f32 v[82:83], v[184:185], v[110:111], v[82:83] op_sel_hi:[1, 0, 1]
	v_mov_b32_e32 v96, v111
	ds_read_b128 v[108:111], v174 offset:272
	v_pk_fma_f32 v[84:85], v[186:187], v[96:97], v[84:85] op_sel_hi:[1, 0, 1]
	v_pk_fma_f32 v[86:87], v[184:185], v[96:97], v[86:87] op_sel_hi:[1, 0, 1]
	v_pk_fma_f32 v[30:31], v[184:185], v[34:35], v[140:141] op_sel:[0, 1, 0]
	v_pk_fma_f32 v[32:33], v[186:187], v[36:37], v[150:151] op_sel_hi:[1, 0, 1]
	s_waitcnt lgkmcnt(0)
	v_pk_fma_f32 v[96:97], v[184:185], v[108:109], v[94:95] op_sel:[0, 1, 0]
	v_mov_b32_e32 v94, v111
	v_pk_fma_f32 v[34:35], v[184:185], v[36:37], v[142:143] op_sel_hi:[1, 0, 1]
	v_pk_fma_f32 v[36:37], v[186:187], v[38:39], v[152:153] op_sel_hi:[1, 0, 1]
	v_pk_fma_f32 v[38:39], v[184:185], v[38:39], v[144:145] op_sel_hi:[1, 0, 1]
	v_pk_fma_f32 v[90:91], v[184:185], v[108:109], v[90:91] op_sel_hi:[1, 0, 1]
	v_pk_fma_f32 v[100:101], v[184:185], v[110:111], v[100:101] op_sel_hi:[1, 0, 1]
	v_pk_fma_f32 v[104:105], v[184:185], v[94:95], v[104:105] op_sel_hi:[1, 0, 1]
	v_add_co_u32_e64 v0, s[42:43], s3, v22
	v_pk_fma_f32 v[64:65], v[186:187], v[114:115], v[64:65] op_sel_hi:[1, 0, 1]
	s_nop 0
	v_addc_co_u32_e64 v1, s[42:43], 0, v23, s[42:43]
	v_pk_fma_f32 v[88:89], v[186:187], v[108:109], v[88:89] op_sel_hi:[1, 0, 1]
	v_pk_fma_f32 v[92:93], v[186:187], v[108:109], v[92:93] op_sel:[0, 1, 0]
	v_pk_fma_f32 v[98:99], v[186:187], v[110:111], v[98:99] op_sel_hi:[1, 0, 1]
	v_pk_fma_f32 v[102:103], v[186:187], v[94:95], v[102:103] op_sel_hi:[1, 0, 1]
	s_waitcnt vmcnt(4)
	v_pk_fma_f32 v[94:95], v[190:191], v[116:117], v[24:25] op_sel_hi:[1, 0, 1]
	v_mov_b32_e32 v24, v119
	v_pk_fma_f32 v[108:109], v[188:189], v[116:117], v[26:27] op_sel_hi:[1, 0, 1]
	v_pk_fma_f32 v[110:111], v[190:191], v[116:117], v[28:29] op_sel:[0, 1, 0]
	v_pk_fma_f32 v[112:113], v[188:189], v[116:117], v[30:31] op_sel:[0, 1, 0]
	v_pk_fma_f32 v[114:115], v[190:191], v[118:119], v[32:33] op_sel_hi:[1, 0, 1]
	v_pk_fma_f32 v[116:117], v[188:189], v[118:119], v[34:35] op_sel_hi:[1, 0, 1]
	v_pk_fma_f32 v[118:119], v[190:191], v[24:25], v[36:37] op_sel_hi:[1, 0, 1]
	v_pk_fma_f32 v[120:121], v[188:189], v[24:25], v[38:39] op_sel_hi:[1, 0, 1]
	ds_read_b128 v[24:27], v174 offset:304
	ds_read_b128 v[34:37], v174 offset:320
	s_waitcnt lgkmcnt(1)
	v_pk_fma_f32 v[40:41], v[190:191], v[24:25], v[40:41] op_sel_hi:[1, 0, 1]
	v_pk_fma_f32 v[42:43], v[188:189], v[24:25], v[42:43] op_sel_hi:[1, 0, 1]
	v_pk_fma_f32 v[44:45], v[190:191], v[24:25], v[44:45] op_sel:[0, 1, 0]
	v_pk_fma_f32 v[46:47], v[188:189], v[24:25], v[46:47] op_sel:[0, 1, 0]
	v_pk_fma_f32 v[48:49], v[190:191], v[26:27], v[48:49] op_sel_hi:[1, 0, 1]
	v_pk_fma_f32 v[50:51], v[188:189], v[26:27], v[50:51] op_sel_hi:[1, 0, 1]
	v_mov_b32_e32 v24, v27
	s_waitcnt lgkmcnt(0)
	v_pk_fma_f32 v[26:27], v[188:189], v[34:35], v[122:123] op_sel_hi:[1, 0, 1]
	v_pk_fma_f32 v[28:29], v[190:191], v[34:35], v[124:125] op_sel:[0, 1, 0]
	ds_read_b128 v[122:125], v174 offset:336
	v_pk_fma_f32 v[52:53], v[190:191], v[24:25], v[52:53] op_sel_hi:[1, 0, 1]
	v_pk_fma_f32 v[54:55], v[188:189], v[24:25], v[54:55] op_sel_hi:[1, 0, 1]
	v_pk_fma_f32 v[24:25], v[190:191], v[34:35], v[106:107] op_sel_hi:[1, 0, 1]
	v_mov_b32_e32 v38, v37
	s_waitcnt lgkmcnt(0)
	v_pk_fma_f32 v[56:57], v[190:191], v[122:123], v[56:57] op_sel_hi:[1, 0, 1]
	v_pk_fma_f32 v[58:59], v[188:189], v[122:123], v[58:59] op_sel_hi:[1, 0, 1]
	v_pk_fma_f32 v[60:61], v[190:191], v[122:123], v[60:61] op_sel:[0, 1, 0]
	v_pk_fma_f32 v[62:63], v[188:189], v[122:123], v[62:63] op_sel:[0, 1, 0]
	v_pk_fma_f32 v[64:65], v[190:191], v[124:125], v[64:65] op_sel_hi:[1, 0, 1]
	v_pk_fma_f32 v[66:67], v[188:189], v[124:125], v[66:67] op_sel_hi:[1, 0, 1]
	v_mov_b32_e32 v106, v125
	ds_read_b128 v[122:125], v174 offset:352
	v_pk_fma_f32 v[68:69], v[190:191], v[106:107], v[68:69] op_sel_hi:[1, 0, 1]
	v_pk_fma_f32 v[70:71], v[188:189], v[106:107], v[70:71] op_sel_hi:[1, 0, 1]
	v_pk_fma_f32 v[30:31], v[188:189], v[34:35], v[126:127] op_sel:[0, 1, 0]
	v_pk_fma_f32 v[32:33], v[190:191], v[36:37], v[128:129] op_sel_hi:[1, 0, 1]
	s_waitcnt lgkmcnt(0)
; #define LAS __attribute__((address_space(3)))
; __device__ __forceinline__ void gemv24_item(const float* W, int N, int j0, LAS float* sc, LAS float* red, float (&res)[6], const int tid) {
;     ...
;     for (int kk = 0; kk < 64; ++kk) {
;         const f32x4 wv = *(const f32x4*)(w + (size_t)kk * N);
;         const LAS f32x4* s4 = (const LAS f32x4*)(sc + (ks * 64 + kk) * 24);
; #pragma unroll
;         for (int b4 = 0; b4 < 6; ++b4) { const f32x4 s = s4[b4]; acc[4 * b4] += wv * s[0]; acc[4 * b4 + 1] += wv * s[1]; acc[4 * b4 + 2] += wv * s[2]; acc[4 * b4 + 3] += wv * s[3]; }
	v_pk_fma_f32 v[72:73], v[190:191], v[122:123], v[72:73] op_sel_hi:[1, 0, 1]
	v_pk_fma_f32 v[74:75], v[188:189], v[122:123], v[74:75] op_sel_hi:[1, 0, 1]
	v_pk_fma_f32 v[76:77], v[190:191], v[122:123], v[76:77] op_sel:[0, 1, 0]
	v_pk_fma_f32 v[78:79], v[188:189], v[122:123], v[78:79] op_sel:[0, 1, 0]
	v_pk_fma_f32 v[80:81], v[190:191], v[124:125], v[80:81] op_sel_hi:[1, 0, 1]
	v_pk_fma_f32 v[82:83], v[188:189], v[124:125], v[82:83] op_sel_hi:[1, 0, 1]
	v_mov_b32_e32 v106, v125
	ds_read_b128 v[122:125], v174 offset:368
	v_pk_fma_f32 v[84:85], v[190:191], v[106:107], v[84:85] op_sel_hi:[1, 0, 1]
	v_pk_fma_f32 v[86:87], v[188:189], v[106:107], v[86:87] op_sel_hi:[1, 0, 1]
	v_pk_fma_f32 v[34:35], v[188:189], v[36:37], v[130:131] op_sel_hi:[1, 0, 1]
	v_pk_fma_f32 v[36:37], v[190:191], v[38:39], v[132:133] op_sel_hi:[1, 0, 1]
	s_waitcnt lgkmcnt(0)
	v_mov_b32_e32 v106, v125
	v_pk_fma_f32 v[38:39], v[188:189], v[38:39], v[134:135] op_sel_hi:[1, 0, 1]
	v_pk_fma_f32 v[90:91], v[188:189], v[122:123], v[90:91] op_sel_hi:[1, 0, 1]
	v_pk_fma_f32 v[96:97], v[188:189], v[122:123], v[96:97] op_sel:[0, 1, 0]
	v_pk_fma_f32 v[100:101], v[188:189], v[124:125], v[100:101] op_sel_hi:[1, 0, 1]
	v_pk_fma_f32 v[104:105], v[188:189], v[106:107], v[104:105] op_sel_hi:[1, 0, 1]
	v_add_co_u32_e64 v0, s[42:43], s0, v22
	v_pk_fma_f32 v[88:89], v[190:191], v[122:123], v[88:89] op_sel_hi:[1, 0, 1]
	s_nop 0
	v_addc_co_u32_e64 v1, s[42:43], 0, v23, s[42:43]
	v_pk_fma_f32 v[92:93], v[190:191], v[122:123], v[92:93] op_sel:[0, 1, 0]
	v_pk_fma_f32 v[98:99], v[190:191], v[124:125], v[98:99] op_sel_hi:[1, 0, 1]
	v_pk_fma_f32 v[102:103], v[190:191], v[106:107], v[102:103] op_sel_hi:[1, 0, 1]
	ds_read_b128 v[122:125], v174 offset:384
	s_mov_b32 s0, 0x2d000
	s_waitcnt vmcnt(3) lgkmcnt(0)
	v_pk_fma_f32 v[106:107], v[194:195], v[122:123], v[94:95] op_sel_hi:[1, 0, 1]
	v_mov_b32_e32 v94, v125
	v_pk_fma_f32 v[108:109], v[192:193], v[122:123], v[108:109] op_sel_hi:[1, 0, 1]
	v_pk_fma_f32 v[110:111], v[194:195], v[122:123], v[110:111] op_sel:[0, 1, 0]
	v_pk_fma_f32 v[112:113], v[192:193], v[122:123], v[112:113] op_sel:[0, 1, 0]
	v_pk_fma_f32 v[128:129], v[192:193], v[94:95], v[120:121] op_sel_hi:[1, 0, 1]
	ds_read_b128 v[120:123], v174 offset:400
	v_pk_fma_f32 v[118:119], v[194:195], v[94:95], v[118:119] op_sel_hi:[1, 0, 1]
	v_pk_fma_f32 v[116:117], v[192:193], v[124:125], v[116:117] op_sel_hi:[1, 0, 1]
	v_pk_fma_f32 v[114:115], v[194:195], v[124:125], v[114:115] op_sel_hi:[1, 0, 1]
	s_waitcnt lgkmcnt(0)
	v_pk_fma_f32 v[144:145], v[194:195], v[120:121], v[40:41] op_sel_hi:[1, 0, 1]
	v_mov_b32_e32 v40, v123
	v_pk_fma_f32 v[146:147], v[192:193], v[120:121], v[42:43] op_sel_hi:[1, 0, 1]
	v_pk_fma_f32 v[44:45], v[194:195], v[120:121], v[44:45] op_sel:[0, 1, 0]
	v_pk_fma_f32 v[46:47], v[192:193], v[120:121], v[46:47] op_sel:[0, 1, 0]
	v_pk_fma_f32 v[48:49], v[194:195], v[122:123], v[48:49] op_sel_hi:[1, 0, 1]
	v_pk_fma_f32 v[50:51], v[192:193], v[122:123], v[50:51] op_sel_hi:[1, 0, 1]
	v_pk_fma_f32 v[52:53], v[194:195], v[40:41], v[52:53] op_sel_hi:[1, 0, 1]
	v_pk_fma_f32 v[54:55], v[192:193], v[40:41], v[54:55] op_sel_hi:[1, 0, 1]
	ds_read_b128 v[40:43], v174 offset:416
	ds_read_b128 v[120:123], v174 offset:432
	s_waitcnt lgkmcnt(1)
	v_pk_fma_f32 v[148:149], v[194:195], v[40:41], v[24:25] op_sel_hi:[1, 0, 1]
	v_pk_fma_f32 v[150:151], v[192:193], v[40:41], v[26:27] op_sel_hi:[1, 0, 1]
	v_mov_b32_e32 v24, v43
	s_waitcnt lgkmcnt(0)
	v_pk_fma_f32 v[26:27], v[192:193], v[120:121], v[58:59] op_sel_hi:[1, 0, 1]
	v_mov_b32_e32 v58, v123
	v_pk_fma_f32 v[152:153], v[194:195], v[40:41], v[28:29] op_sel:[0, 1, 0]
	v_pk_fma_f32 v[36:37], v[194:195], v[24:25], v[36:37] op_sel_hi:[1, 0, 1]
	v_pk_fma_f32 v[38:39], v[192:193], v[24:25], v[38:39] op_sel_hi:[1, 0, 1]
	v_pk_fma_f32 v[24:25], v[194:195], v[120:121], v[56:57] op_sel_hi:[1, 0, 1]
	v_pk_fma_f32 v[28:29], v[194:195], v[120:121], v[60:61] op_sel:[0, 1, 0]
	v_pk_fma_f32 v[56:57], v[194:195], v[58:59], v[68:69] op_sel_hi:[1, 0, 1]
	v_pk_fma_f32 v[130:131], v[192:193], v[58:59], v[70:71] op_sel_hi:[1, 0, 1]
	ds_read_b128 v[58:61], v174 offset:448
	v_pk_fma_f32 v[154:155], v[192:193], v[40:41], v[30:31] op_sel:[0, 1, 0]
	v_pk_fma_f32 v[32:33], v[194:195], v[42:43], v[32:33] op_sel_hi:[1, 0, 1]
	v_pk_fma_f32 v[34:35], v[192:193], v[42:43], v[34:35] op_sel_hi:[1, 0, 1]
	v_pk_fma_f32 v[40:41], v[194:195], v[122:123], v[64:65] op_sel_hi:[1, 0, 1]
	v_pk_fma_f32 v[42:43], v[192:193], v[122:123], v[66:67] op_sel_hi:[1, 0, 1]
	ds_read_b128 v[64:67], v174 offset:496
	s_waitcnt lgkmcnt(1)
	v_pk_fma_f32 v[72:73], v[194:195], v[58:59], v[72:73] op_sel_hi:[1, 0, 1]
	v_pk_fma_f32 v[74:75], v[192:193], v[58:59], v[74:75] op_sel_hi:[1, 0, 1]
	v_pk_fma_f32 v[132:133], v[194:195], v[58:59], v[76:77] op_sel:[0, 1, 0]
	v_pk_fma_f32 v[134:135], v[192:193], v[58:59], v[78:79] op_sel:[0, 1, 0]
	v_mov_b32_e32 v58, v61
	v_pk_fma_f32 v[136:137], v[194:195], v[60:61], v[80:81] op_sel_hi:[1, 0, 1]
	v_pk_fma_f32 v[138:139], v[192:193], v[60:61], v[82:83] op_sel_hi:[1, 0, 1]
	v_pk_fma_f32 v[140:141], v[194:195], v[58:59], v[84:85] op_sel_hi:[1, 0, 1]
	v_pk_fma_f32 v[142:143], v[192:193], v[58:59], v[86:87] op_sel_hi:[1, 0, 1]
	ds_read_b128 v[58:61], v174 offset:464
	v_pk_fma_f32 v[30:31], v[192:193], v[120:121], v[62:63] op_sel:[0, 1, 0]
	s_waitcnt lgkmcnt(0)
; #define LAS __attribute__((address_space(3)))
; __device__ __forceinline__ void gemv24_item(const float* W, int N, int j0, LAS float* sc, LAS float* red, float (&res)[6], const int tid) {
;     ...
;     for (int kk = 0; kk < 64; ++kk) {
;         const f32x4 wv = *(const f32x4*)(w + (size_t)kk * N);
;         const LAS f32x4* s4 = (const LAS f32x4*)(sc + (ks * 64 + kk) * 24);
; #pragma unroll
;         for (int b4 = 0; b4 < 6; ++b4) { const f32x4 s = s4[b4]; acc[4 * b4] += wv * s[0]; acc[4 * b4 + 1] += wv * s[1]; acc[4 * b4 + 2] += wv * s[2]; acc[4 * b4 + 3] += wv * s[3]; }
	v_pk_fma_f32 v[80:81], v[194:195], v[58:59], v[88:89] op_sel_hi:[1, 0, 1]
	v_pk_fma_f32 v[84:85], v[192:193], v[58:59], v[90:91] op_sel_hi:[1, 0, 1]
	v_pk_fma_f32 v[94:95], v[194:195], v[58:59], v[92:93] op_sel:[0, 1, 0]
	v_pk_fma_f32 v[96:97], v[192:193], v[58:59], v[96:97] op_sel:[0, 1, 0]
	v_mov_b32_e32 v58, v61
	v_pk_fma_f32 v[122:123], v[192:193], v[60:61], v[100:101] op_sel_hi:[1, 0, 1]
	v_pk_fma_f32 v[126:127], v[192:193], v[58:59], v[104:105] op_sel_hi:[1, 0, 1]
	v_add_co_u32_e64 v0, s[42:43], s0, v22
	v_pk_fma_f32 v[120:121], v[194:195], v[60:61], v[98:99] op_sel_hi:[1, 0, 1]
	s_nop 0
	v_addc_co_u32_e64 v1, s[42:43], 0, v23, s[42:43]
	v_pk_fma_f32 v[124:125], v[194:195], v[58:59], v[102:103] op_sel_hi:[1, 0, 1]
	ds_read_b128 v[58:61], v174 offset:480
	s_mov_b32 s0, 0x36000
	s_waitcnt vmcnt(2)
	v_pk_fma_f32 v[62:63], v[198:199], v[64:65], v[44:45] op_sel:[0, 1, 0]
	v_mov_b32_e32 v44, v67
	v_pk_fma_f32 v[92:93], v[196:197], v[66:67], v[50:51] op_sel_hi:[1, 0, 1]
	v_pk_fma_f32 v[98:99], v[198:199], v[44:45], v[52:53] op_sel_hi:[1, 0, 1]
	ds_read_b128 v[50:53], v174 offset:512
	s_waitcnt lgkmcnt(1)
	v_pk_fma_f32 v[82:83], v[196:197], v[58:59], v[108:109] op_sel_hi:[1, 0, 1]
	v_pk_fma_f32 v[86:87], v[198:199], v[58:59], v[110:111] op_sel:[0, 1, 0]
	ds_read_b128 v[108:111], v174 offset:528
	v_pk_fma_f32 v[90:91], v[198:199], v[66:67], v[48:49] op_sel_hi:[1, 0, 1]
	s_waitcnt lgkmcnt(1)
	v_pk_fma_f32 v[66:67], v[198:199], v[52:53], v[32:33] op_sel_hi:[1, 0, 1]
	v_mov_b32_e32 v32, v53
	v_pk_fma_f32 v[78:79], v[198:199], v[58:59], v[106:107] op_sel_hi:[1, 0, 1]
	v_pk_fma_f32 v[88:89], v[196:197], v[58:59], v[112:113] op_sel:[0, 1, 0]
	v_pk_fma_f32 v[100:101], v[198:199], v[60:61], v[114:115] op_sel_hi:[1, 0, 1]
	v_pk_fma_f32 v[102:103], v[196:197], v[60:61], v[116:117] op_sel_hi:[1, 0, 1]
	v_mov_b32_e32 v58, v61
	v_pk_fma_f32 v[70:71], v[198:199], v[32:33], v[36:37] op_sel_hi:[1, 0, 1]
	v_pk_fma_f32 v[76:77], v[196:197], v[32:33], v[38:39] op_sel_hi:[1, 0, 1]
	ds_read_b128 v[114:117], v174 offset:544
	s_waitcnt lgkmcnt(1)
	v_pk_fma_f32 v[32:33], v[198:199], v[108:109], v[24:25] op_sel_hi:[1, 0, 1]
	v_mov_b32_e32 v24, v111
	v_pk_fma_f32 v[112:113], v[196:197], v[58:59], v[128:129] op_sel_hi:[1, 0, 1]
	v_pk_fma_f32 v[68:69], v[196:197], v[52:53], v[34:35] op_sel_hi:[1, 0, 1]
	v_pk_fma_f32 v[34:35], v[196:197], v[108:109], v[26:27] op_sel_hi:[1, 0, 1]
	v_pk_fma_f32 v[36:37], v[198:199], v[108:109], v[28:29] op_sel:[0, 1, 0]
	v_pk_fma_f32 v[38:39], v[196:197], v[108:109], v[30:31] op_sel:[0, 1, 0]
	v_pk_fma_f32 v[108:109], v[196:197], v[24:25], v[130:131] op_sel_hi:[1, 0, 1]
	ds_read_b128 v[128:131], v174 offset:560
	v_pk_fma_f32 v[104:105], v[196:197], v[44:45], v[54:55] op_sel_hi:[1, 0, 1]
	v_pk_fma_f32 v[52:53], v[198:199], v[110:111], v[40:41] op_sel_hi:[1, 0, 1]
	v_pk_fma_f32 v[54:55], v[196:197], v[110:111], v[42:43] op_sel_hi:[1, 0, 1]
	s_waitcnt lgkmcnt(1)
	v_pk_fma_f32 v[26:27], v[196:197], v[114:115], v[74:75] op_sel_hi:[1, 0, 1]
	v_pk_fma_f32 v[30:31], v[196:197], v[114:115], v[134:135] op_sel:[0, 1, 0]
	v_pk_fma_f32 v[40:41], v[198:199], v[116:117], v[136:137] op_sel_hi:[1, 0, 1]
	v_mov_b32_e32 v74, v117
	ds_read_b128 v[134:137], v174 offset:704
	s_waitcnt lgkmcnt(1)
	v_pk_fma_f32 v[110:111], v[198:199], v[128:129], v[80:81] op_sel_hi:[1, 0, 1]
	v_mov_b32_e32 v80, v131
	v_pk_fma_f32 v[106:107], v[198:199], v[58:59], v[118:119] op_sel_hi:[1, 0, 1]
	v_pk_fma_f32 v[58:59], v[198:199], v[64:65], v[144:145] op_sel_hi:[1, 0, 1]
	v_pk_fma_f32 v[60:61], v[196:197], v[64:65], v[146:147] op_sel_hi:[1, 0, 1]
	v_pk_fma_f32 v[64:65], v[196:197], v[64:65], v[46:47] op_sel:[0, 1, 0]
	v_pk_fma_f32 v[44:45], v[198:199], v[50:51], v[148:149] op_sel_hi:[1, 0, 1]
	v_pk_fma_f32 v[46:47], v[196:197], v[50:51], v[150:151] op_sel_hi:[1, 0, 1]
	v_pk_fma_f32 v[48:49], v[198:199], v[50:51], v[152:153] op_sel:[0, 1, 0]
	v_pk_fma_f32 v[50:51], v[196:197], v[50:51], v[154:155] op_sel:[0, 1, 0]
	v_pk_fma_f32 v[56:57], v[198:199], v[24:25], v[56:57] op_sel_hi:[1, 0, 1]
	v_pk_fma_f32 v[24:25], v[198:199], v[114:115], v[72:73] op_sel_hi:[1, 0, 1]
	v_pk_fma_f32 v[28:29], v[198:199], v[114:115], v[132:133] op_sel:[0, 1, 0]
	v_pk_fma_f32 v[42:43], v[196:197], v[116:117], v[138:139] op_sel_hi:[1, 0, 1]
	v_pk_fma_f32 v[72:73], v[198:199], v[74:75], v[140:141] op_sel_hi:[1, 0, 1]
	v_pk_fma_f32 v[74:75], v[196:197], v[74:75], v[142:143] op_sel_hi:[1, 0, 1]
	v_pk_fma_f32 v[114:115], v[196:197], v[128:129], v[84:85] op_sel_hi:[1, 0, 1]
	v_pk_fma_f32 v[118:119], v[196:197], v[128:129], v[96:97] op_sel:[0, 1, 0]
	v_pk_fma_f32 v[122:123], v[196:197], v[130:131], v[122:123] op_sel_hi:[1, 0, 1]
	v_pk_fma_f32 v[126:127], v[196:197], v[80:81], v[126:127] op_sel_hi:[1, 0, 1]
	v_add_co_u32_e64 v0, s[42:43], s0, v22
	v_pk_fma_f32 v[116:117], v[198:199], v[128:129], v[94:95] op_sel:[0, 1, 0]
	s_nop 0
	v_addc_co_u32_e64 v1, s[42:43], 0, v23, s[42:43]
	v_pk_fma_f32 v[120:121], v[198:199], v[130:131], v[120:121] op_sel_hi:[1, 0, 1]
	v_pk_fma_f32 v[124:125], v[198:199], v[80:81], v[124:125] op_sel_hi:[1, 0, 1]
	ds_read_b128 v[128:131], v174 offset:576
	s_mov_b32 s0, 0x3f000
	s_waitcnt vmcnt(1) lgkmcnt(0)
	v_pk_fma_f32 v[80:81], v[202:203], v[128:129], v[78:79] op_sel_hi:[1, 0, 1]
	v_pk_fma_f32 v[84:85], v[200:201], v[128:129], v[82:83] op_sel_hi:[1, 0, 1]
	v_pk_fma_f32 v[94:95], v[202:203], v[128:129], v[86:87] op_sel:[0, 1, 0]
	v_pk_fma_f32 v[96:97], v[200:201], v[128:129], v[88:89] op_sel:[0, 1, 0]
	v_pk_fma_f32 v[100:101], v[202:203], v[130:131], v[100:101] op_sel_hi:[1, 0, 1]
	v_pk_fma_f32 v[102:103], v[200:201], v[130:131], v[102:103] op_sel_hi:[1, 0, 1]
	v_mov_b32_e32 v78, v131
	ds_read_b128 v[128:131], v174 offset:592
	v_pk_fma_f32 v[106:107], v[202:203], v[78:79], v[106:107] op_sel_hi:[1, 0, 1]
	v_pk_fma_f32 v[112:113], v[200:201], v[78:79], v[112:113] op_sel_hi:[1, 0, 1]
	s_waitcnt lgkmcnt(0)
; #define LAS __attribute__((address_space(3)))
; __device__ __forceinline__ void gemv24_item(const float* W, int N, int j0, LAS float* sc, LAS float* red, float (&res)[6], const int tid) {
;     ...
;     for (int kk = 0; kk < 64; ++kk) {
;         const f32x4 wv = *(const f32x4*)(w + (size_t)kk * N);
;         const LAS f32x4* s4 = (const LAS f32x4*)(sc + (ks * 64 + kk) * 24);
; #pragma unroll
;         for (int b4 = 0; b4 < 6; ++b4) { const f32x4 s = s4[b4]; acc[4 * b4] += wv * s[0]; acc[4 * b4 + 1] += wv * s[1]; acc[4 * b4 + 2] += wv * s[2]; acc[4 * b4 + 3] += wv * s[3]; }
	v_pk_fma_f32 v[78:79], v[202:203], v[128:129], v[58:59] op_sel_hi:[1, 0, 1]
	v_pk_fma_f32 v[82:83], v[200:201], v[128:129], v[60:61] op_sel_hi:[1, 0, 1]
	v_pk_fma_f32 v[86:87], v[202:203], v[128:129], v[62:63] op_sel:[0, 1, 0]
	v_pk_fma_f32 v[88:89], v[200:201], v[128:129], v[64:65] op_sel:[0, 1, 0]
	v_pk_fma_f32 v[90:91], v[202:203], v[130:131], v[90:91] op_sel_hi:[1, 0, 1]
	v_pk_fma_f32 v[92:93], v[200:201], v[130:131], v[92:93] op_sel_hi:[1, 0, 1]
	v_mov_b32_e32 v58, v131
	ds_read_b128 v[128:131], v174 offset:608
	v_pk_fma_f32 v[98:99], v[202:203], v[58:59], v[98:99] op_sel_hi:[1, 0, 1]
	v_pk_fma_f32 v[104:105], v[200:201], v[58:59], v[104:105] op_sel_hi:[1, 0, 1]
	s_waitcnt lgkmcnt(0)
	v_pk_fma_f32 v[58:59], v[202:203], v[128:129], v[44:45] op_sel_hi:[1, 0, 1]
	v_pk_fma_f32 v[60:61], v[200:201], v[128:129], v[46:47] op_sel_hi:[1, 0, 1]
	v_pk_fma_f32 v[62:63], v[202:203], v[128:129], v[48:49] op_sel:[0, 1, 0]
	v_pk_fma_f32 v[64:65], v[200:201], v[128:129], v[50:51] op_sel:[0, 1, 0]
	v_pk_fma_f32 v[66:67], v[202:203], v[130:131], v[66:67] op_sel_hi:[1, 0, 1]
	v_pk_fma_f32 v[68:69], v[200:201], v[130:131], v[68:69] op_sel_hi:[1, 0, 1]
	v_mov_b32_e32 v44, v131
	ds_read_b128 v[128:131], v174 offset:624
	v_pk_fma_f32 v[70:71], v[202:203], v[44:45], v[70:71] op_sel_hi:[1, 0, 1]
	v_pk_fma_f32 v[76:77], v[200:201], v[44:45], v[76:77] op_sel_hi:[1, 0, 1]
	s_waitcnt lgkmcnt(0)
	v_pk_fma_f32 v[44:45], v[202:203], v[128:129], v[32:33] op_sel_hi:[1, 0, 1]
	v_pk_fma_f32 v[46:47], v[200:201], v[128:129], v[34:35] op_sel_hi:[1, 0, 1]
	v_pk_fma_f32 v[48:49], v[202:203], v[128:129], v[36:37] op_sel:[0, 1, 0]
	v_pk_fma_f32 v[50:51], v[200:201], v[128:129], v[38:39] op_sel:[0, 1, 0]
	v_pk_fma_f32 v[52:53], v[202:203], v[130:131], v[52:53] op_sel_hi:[1, 0, 1]
	v_pk_fma_f32 v[54:55], v[200:201], v[130:131], v[54:55] op_sel_hi:[1, 0, 1]
	v_mov_b32_e32 v32, v131
	ds_read_b128 v[128:131], v174 offset:640
	v_pk_fma_f32 v[56:57], v[202:203], v[32:33], v[56:57] op_sel_hi:[1, 0, 1]
	v_pk_fma_f32 v[132:133], v[200:201], v[32:33], v[108:109] op_sel_hi:[1, 0, 1]
	s_waitcnt lgkmcnt(0)
	v_pk_fma_f32 v[32:33], v[202:203], v[128:129], v[24:25] op_sel_hi:[1, 0, 1]
	v_mov_b32_e32 v24, v131
	v_pk_fma_f32 v[34:35], v[200:201], v[128:129], v[26:27] op_sel_hi:[1, 0, 1]
	v_pk_fma_f32 v[36:37], v[202:203], v[128:129], v[28:29] op_sel:[0, 1, 0]
	v_pk_fma_f32 v[38:39], v[200:201], v[128:129], v[30:31] op_sel:[0, 1, 0]
	v_pk_fma_f32 v[40:41], v[202:203], v[130:131], v[40:41] op_sel_hi:[1, 0, 1]
	v_pk_fma_f32 v[42:43], v[200:201], v[130:131], v[42:43] op_sel_hi:[1, 0, 1]
	v_pk_fma_f32 v[128:129], v[202:203], v[24:25], v[72:73] op_sel_hi:[1, 0, 1]
	v_pk_fma_f32 v[130:131], v[200:201], v[24:25], v[74:75] op_sel_hi:[1, 0, 1]
	ds_read_b128 v[72:75], v174 offset:656
	s_waitcnt lgkmcnt(0)
	v_pk_fma_f32 v[24:25], v[202:203], v[72:73], v[110:111] op_sel_hi:[1, 0, 1]
	v_pk_fma_f32 v[26:27], v[200:201], v[72:73], v[114:115] op_sel_hi:[1, 0, 1]
	v_pk_fma_f32 v[28:29], v[202:203], v[72:73], v[116:117] op_sel:[0, 1, 0]
	v_pk_fma_f32 v[30:31], v[200:201], v[72:73], v[118:119] op_sel:[0, 1, 0]
	v_mov_b32_e32 v72, v75
	v_pk_fma_f32 v[122:123], v[200:201], v[74:75], v[122:123] op_sel_hi:[1, 0, 1]
	v_pk_fma_f32 v[126:127], v[200:201], v[72:73], v[126:127] op_sel_hi:[1, 0, 1]
	v_add_co_u32_e64 v0, s[42:43], s0, v22
	v_pk_fma_f32 v[120:121], v[202:203], v[74:75], v[120:121] op_sel_hi:[1, 0, 1]
	s_nop 0
	v_addc_co_u32_e64 v1, s[42:43], 0, v23, s[42:43]
	v_pk_fma_f32 v[124:125], v[202:203], v[72:73], v[124:125] op_sel_hi:[1, 0, 1]
	ds_read_b128 v[72:75], v174 offset:672
	s_waitcnt lgkmcnt(0)
	v_mov_b32_e32 v22, v75
	s_waitcnt vmcnt(0)
	v_pk_fma_f32 v[118:119], v[206:207], v[72:73], v[80:81] op_sel_hi:[1, 0, 1]
	v_pk_fma_f32 v[116:117], v[204:205], v[72:73], v[84:85] op_sel_hi:[1, 0, 1]
	v_pk_fma_f32 v[110:111], v[206:207], v[72:73], v[94:95] op_sel:[0, 1, 0]
	v_pk_fma_f32 v[108:109], v[204:205], v[72:73], v[96:97] op_sel:[0, 1, 0]
	v_pk_fma_f32 v[100:101], v[206:207], v[74:75], v[100:101] op_sel_hi:[1, 0, 1]
	v_pk_fma_f32 v[96:97], v[204:205], v[74:75], v[102:103] op_sel_hi:[1, 0, 1]
	ds_read_b128 v[72:75], v174 offset:688
	v_pk_fma_f32 v[84:85], v[206:207], v[22:23], v[106:107] op_sel_hi:[1, 0, 1]
	v_pk_fma_f32 v[80:81], v[204:205], v[22:23], v[112:113] op_sel_hi:[1, 0, 1]
	v_pk_fma_f32 v[68:69], v[204:205], v[136:137], v[68:69] op_sel_hi:[1, 0, 1]
	s_waitcnt lgkmcnt(0)
; #define LAS __attribute__((address_space(3)))
; __device__ __forceinline__ void gemv24_item(const float* W, int N, int j0, LAS float* sc, LAS float* red, float (&res)[6], const int tid) {
;     ...
;     for (int kk = 0; kk < 64; ++kk) {
;         const f32x4 wv = *(const f32x4*)(w + (size_t)kk * N);
;         const LAS f32x4* s4 = (const LAS f32x4*)(sc + (ks * 64 + kk) * 24);
; #pragma unroll
;         for (int b4 = 0; b4 < 6; ++b4) { const f32x4 s = s4[b4]; acc[4 * b4] += wv * s[0]; acc[4 * b4 + 1] += wv * s[1]; acc[4 * b4 + 2] += wv * s[2]; acc[4 * b4 + 3] += wv * s[3]; }
;     }
; #pragma unroll
;     for (int bg = 0; bg < 3; ++bg) {
; #pragma unroll
;         for (int bb = 0; bb < 8; ++bb) {
;             f32x4 a = acc[8 * bg + bb];
;             a[0] += __shfl_xor(a[0], 32); a[1] += __shfl_xor(a[1], 32); a[2] += __shfl_xor(a[2], 32); a[3] += __shfl_xor(a[3], 32);
;             if (lane < 32) *(LAS f32x4*)(red + ((wave * 8 + bb) * 128 + cg * 4)) = a;
	v_mov_b32_e32 v22, v75
	v_pk_fma_f32 v[114:115], v[206:207], v[72:73], v[78:79] op_sel_hi:[1, 0, 1]
	v_pk_fma_f32 v[112:113], v[204:205], v[72:73], v[82:83] op_sel_hi:[1, 0, 1]
	v_pk_fma_f32 v[106:107], v[206:207], v[72:73], v[86:87] op_sel:[0, 1, 0]
	v_pk_fma_f32 v[102:103], v[204:205], v[72:73], v[88:89] op_sel:[0, 1, 0]
	v_pk_fma_f32 v[94:95], v[206:207], v[74:75], v[90:91] op_sel_hi:[1, 0, 1]
	v_pk_fma_f32 v[90:91], v[204:205], v[74:75], v[92:93] op_sel_hi:[1, 0, 1]
	v_pk_fma_f32 v[78:79], v[206:207], v[22:23], v[98:99] op_sel_hi:[1, 0, 1]
	v_pk_fma_f32 v[74:75], v[204:205], v[22:23], v[104:105] op_sel_hi:[1, 0, 1]
	v_pk_fma_f32 v[104:105], v[206:207], v[134:135], v[58:59] op_sel_hi:[1, 0, 1]
	v_pk_fma_f32 v[98:99], v[204:205], v[134:135], v[60:61] op_sel_hi:[1, 0, 1]
	v_pk_fma_f32 v[88:89], v[206:207], v[134:135], v[62:63] op_sel:[0, 1, 0]
	v_pk_fma_f32 v[82:83], v[204:205], v[134:135], v[64:65] op_sel:[0, 1, 0]
	v_pk_fma_f32 v[72:73], v[206:207], v[136:137], v[66:67] op_sel_hi:[1, 0, 1]
	v_mov_b32_e32 v22, v137
	ds_read_b128 v[134:137], v174 offset:720
	v_pk_fma_f32 v[62:63], v[206:207], v[22:23], v[70:71] op_sel_hi:[1, 0, 1]
	v_pk_fma_f32 v[60:61], v[204:205], v[22:23], v[76:77] op_sel_hi:[1, 0, 1]
	s_waitcnt lgkmcnt(0)
	v_mov_b32_e32 v22, v137
	v_pk_fma_f32 v[92:93], v[206:207], v[134:135], v[44:45] op_sel_hi:[1, 0, 1]
	v_pk_fma_f32 v[86:87], v[204:205], v[134:135], v[46:47] op_sel_hi:[1, 0, 1]
	v_pk_fma_f32 v[76:77], v[206:207], v[134:135], v[48:49] op_sel:[0, 1, 0]
	v_pk_fma_f32 v[70:71], v[204:205], v[134:135], v[50:51] op_sel:[0, 1, 0]
	v_pk_fma_f32 v[58:59], v[206:207], v[22:23], v[56:57] op_sel_hi:[1, 0, 1]
	v_pk_fma_f32 v[56:57], v[204:205], v[22:23], v[132:133] op_sel_hi:[1, 0, 1]
	ds_read_b128 v[132:135], v174 offset:736
	v_pk_fma_f32 v[66:67], v[206:207], v[136:137], v[52:53] op_sel_hi:[1, 0, 1]
	v_pk_fma_f32 v[64:65], v[204:205], v[136:137], v[54:55] op_sel_hi:[1, 0, 1]
	s_waitcnt lgkmcnt(0)
	v_mov_b32_e32 v22, v135
	v_pk_fma_f32 v[50:51], v[206:207], v[132:133], v[36:37] op_sel:[0, 1, 0]
	v_pk_fma_f32 v[48:49], v[204:205], v[132:133], v[38:39] op_sel:[0, 1, 0]
	v_pk_fma_f32 v[38:39], v[206:207], v[22:23], v[128:129] op_sel_hi:[1, 0, 1]
	v_pk_fma_f32 v[36:37], v[204:205], v[22:23], v[130:131] op_sel_hi:[1, 0, 1]
	ds_read_b128 v[128:131], v174 offset:752
	v_pk_fma_f32 v[54:55], v[206:207], v[132:133], v[32:33] op_sel_hi:[1, 0, 1]
	v_pk_fma_f32 v[52:53], v[204:205], v[132:133], v[34:35] op_sel_hi:[1, 0, 1]
	v_pk_fma_f32 v[46:47], v[206:207], v[134:135], v[40:41] op_sel_hi:[1, 0, 1]
	v_pk_fma_f32 v[44:45], v[204:205], v[134:135], v[42:43] op_sel_hi:[1, 0, 1]
	s_waitcnt lgkmcnt(0)
	v_mov_b32_e32 v22, v131
	v_pk_fma_f32 v[42:43], v[206:207], v[128:129], v[24:25] op_sel_hi:[1, 0, 1]
	v_pk_fma_f32 v[40:41], v[204:205], v[128:129], v[26:27] op_sel_hi:[1, 0, 1]
	v_pk_fma_f32 v[34:35], v[206:207], v[128:129], v[28:29] op_sel:[0, 1, 0]
	v_pk_fma_f32 v[32:33], v[204:205], v[128:129], v[30:31] op_sel:[0, 1, 0]
	v_pk_fma_f32 v[30:31], v[206:207], v[130:131], v[120:121] op_sel_hi:[1, 0, 1]
	v_pk_fma_f32 v[28:29], v[204:205], v[130:131], v[122:123] op_sel_hi:[1, 0, 1]
	v_pk_fma_f32 v[26:27], v[206:207], v[22:23], v[124:125] op_sel_hi:[1, 0, 1]
	v_pk_fma_f32 v[24:25], v[204:205], v[22:23], v[126:127] op_sel_hi:[1, 0, 1]
	v_add_u32_e32 v174, 0x300, v174
	s_cbranch_scc0 .LBB0_523
	ds_bpermute_b32 v0, v156, v116
	ds_bpermute_b32 v1, v156, v117
	ds_bpermute_b32 v2, v156, v118
	ds_bpermute_b32 v3, v156, v119
	s_and_saveexec_b64 s[30:31], vcc
	s_cbranch_execz .LBB0_526
	s_waitcnt lgkmcnt(0)
	v_pk_add_f32 v[2:3], v[118:119], v[2:3]
	v_pk_add_f32 v[0:1], v[116:117], v[0:1]
	ds_write_b128 v157, v[0:3]
